# v28 + cvt weight f32 loads marked nt (stream-once data should not displace reusable tensors from the memory-side cache)
# baseline (speedup 1.0000x reference)
; __device__ __forceinline__ bf16_t f2bf(float f) { return (bf16_t)(cvt_pk_bf16(f, 0.f) & 0xffffu); }
; __device__ __forceinline__ void cvt_tile(unsigned char* shm, int tid, const float* src, bf16_t* dst, int K, int N, int mode, const float* kscale, int ldd, int t) {
;     bf16_t* T = (bf16_t*)shm;
;     const int nnt = N / 256, nti = t % nnt, kt = t / nnt;
;     { const int k = tid >> 3, n8 = (tid & 7) * 8;
;       const float* s = src + (size_t)(kt * 64 + k) * N + nti * 256 + n8; const float ks = kscale ? kscale[kt * 64 + k] : 1.0f;
;       f32x4 v[8];
; #pragma unroll
;       for (int q = 0; q < 4; ++q) { v[2 * q] = *(const f32x4*)(s + q * 64); v[2 * q + 1] = *(const f32x4*)(s + q * 64 + 4); }
;       asm volatile("" ::: "memory");
; #pragma unroll
;       for (int q = 0; q < 4; ++q)
; #pragma unroll
;           for (int j = 0; j < 4; ++j) { T[(q * 64 + n8 + j) * 72 + k] = f2bf(v[2 * q][j] * ks); T[(q * 64 + n8 + 4 + j) * 72 + k] = f2bf(v[2 * q + 1][j] * ks); } }
;     __syncthreads();
; #pragma unroll
;     for (int q = 0; q < 4; ++q) { const int n = q * 64 + (tid >> 3), k8 = (tid & 7) * 8; const int nn = nti * 256 + n;
;       const int drow = mode == 0 ? nn : ((nn >> 7) * 256 + (nn & 127) + (mode == 2 ? 128 : 0));
;       *(u32x4*)(dst + ((size_t)((drow >> 8) * (K / 64) + kt) * 256 + (drow & 255)) * 64 + k8) = *(const u32x4*)(T + n * 72 + k8); }
;     __syncthreads();
; }
; __device__ __forceinline__ void cvt_ffn_tile(const Params& p, unsigned char* shm, int tid, bf16_t* W, int l, int sub, int t) {
;     const size_t wo = (size_t)(l * 2 + sub) * DM * DFF; const float* gk = p.in[2] + (l * 6 + (sub ? 4 : 0)) * DM;
;     if (t < 704) cvt_tile(shm, tid, p.in[26] + wo, W + W_13, DM, DFF, 1, gk, LDX, t);
;     else if (t < 1408) cvt_tile(shm, tid, p.in[27] + wo, W + W_13, DM, DFF, 2, gk, LDX, t - 704);
;     else cvt_tile(shm, tid, p.in[28] + wo, W + W_2, DFF, DM, 0, nullptr, DFF, t - 1408);
.LBB0_756:
	s_or_b64 exec, exec, s[0:1]
	s_mov_b64 s[0:1], src_shared_base
	s_add_i32 s0, 0, 0x20080
	s_cmp_lg_u32 s0, -1
	s_cselect_b32 s0, s0, 0
	s_cselect_b32 s1, s1, 0
	v_mov_b32_e32 v24, s0
	v_mov_b32_e32 v25, s1
	s_waitcnt lgkmcnt(0)
	s_barrier
	ds_read_b32 v0, v24
	s_mov_b64 s[0:1], -1
	s_waitcnt lgkmcnt(0)
	s_barrier
	v_readfirstlane_b32 s2, v0
	s_cmpk_gt_i32 s2, 0x83f
	s_cbranch_scc1 .LBB0_751
	s_cmpk_gt_i32 s2, 0x2bf
	s_cbranch_scc0 .LBB0_766
	s_cmpk_gt_u32 s2, 0x57f
	s_cbranch_scc0 .LBB0_760
	s_add_i32 s0, s2, 0xfa80
	s_bfe_u32 s1, s0, 0xd0003
	v_lshl_add_u32 v24, s1, 6, v3
	v_ashrrev_i32_e32 v25, 31, v24
	s_lshl_b32 s0, s2, 8
	v_lshlrev_b64 v[24:25], 13, v[24:25]
	s_and_b32 s0, s0, 0x700
	v_lshl_add_u64 v[24:25], s[40:41], 0, v[24:25]
	s_lshl_b32 s48, s0, 2
	v_lshl_add_u64 v[24:25], v[24:25], 0, s[48:49]
	v_lshlrev_b32_e32 v0, 2, v2
	v_lshl_add_u64 v[24:25], v[24:25], 0, v[0:1]
	global_load_dwordx4 v[34:37], v[24:25], off offset:16 nt
	global_load_dwordx4 v[38:41], v[24:25], off nt
	global_load_dwordx4 v[42:45], v[24:25], off offset:272 nt
	global_load_dwordx4 v[46:49], v[24:25], off offset:256 nt
	global_load_dwordx4 v[50:53], v[24:25], off offset:528 nt
	global_load_dwordx4 v[54:57], v[24:25], off offset:512 nt
	global_load_dwordx4 v[58:61], v[24:25], off offset:784 nt
	global_load_dwordx4 v[62:65], v[24:25], off offset:768 nt
	v_add_u32_e32 v33, v28, v29
	s_waitcnt vmcnt(6)
	v_cvt_pk_bf16_f32 v0, v38, v1
	ds_write_b16 v26, v0
	v_cvt_pk_bf16_f32 v0, v34, v1
	ds_write_b16 v27, v0 offset:576
	v_cvt_pk_bf16_f32 v0, v39, v1
	ds_write_b16 v26, v0 offset:144
	v_cvt_pk_bf16_f32 v0, v35, v1
	ds_write_b16 v27, v0 offset:720
	v_cvt_pk_bf16_f32 v0, v40, v1
	ds_write_b16 v26, v0 offset:288
	v_cvt_pk_bf16_f32 v0, v36, v1
	ds_write_b16 v27, v0 offset:864
	v_cvt_pk_bf16_f32 v0, v41, v1
	ds_write_b16 v26, v0 offset:432
	v_cvt_pk_bf16_f32 v0, v37, v1
	ds_write_b16 v27, v0 offset:1008
	s_waitcnt vmcnt(4)
	v_cvt_pk_bf16_f32 v0, v46, v1
	ds_write_b16 v26, v0 offset:9216
	v_cvt_pk_bf16_f32 v0, v42, v1
	ds_write_b16 v27, v0 offset:9792
	v_cvt_pk_bf16_f32 v0, v47, v1
	ds_write_b16 v26, v0 offset:9360
	v_cvt_pk_bf16_f32 v0, v43, v1
	ds_write_b16 v27, v0 offset:9936
	v_cvt_pk_bf16_f32 v0, v48, v1
	ds_write_b16 v26, v0 offset:9504
	v_cvt_pk_bf16_f32 v0, v44, v1
	ds_write_b16 v27, v0 offset:10080
	v_cvt_pk_bf16_f32 v0, v49, v1
	ds_write_b16 v26, v0 offset:9648
	v_cvt_pk_bf16_f32 v0, v45, v1
	ds_write_b16 v27, v0 offset:10224
	s_waitcnt vmcnt(2)
	v_cvt_pk_bf16_f32 v0, v54, v1
	ds_write_b16 v26, v0 offset:18432
	v_cvt_pk_bf16_f32 v0, v50, v1
	ds_write_b16 v27, v0 offset:19008
	v_cvt_pk_bf16_f32 v0, v55, v1
	ds_write_b16 v26, v0 offset:18576
	v_cvt_pk_bf16_f32 v0, v51, v1
	ds_write_b16 v27, v0 offset:19152
	v_cvt_pk_bf16_f32 v0, v56, v1
	ds_write_b16 v26, v0 offset:18720
	v_cvt_pk_bf16_f32 v0, v52, v1
	ds_write_b16 v27, v0 offset:19296
	v_cvt_pk_bf16_f32 v0, v57, v1
	ds_write_b16 v26, v0 offset:18864
	v_cvt_pk_bf16_f32 v0, v53, v1
	ds_write_b16 v27, v0 offset:19440
	s_waitcnt vmcnt(0)
	v_cvt_pk_bf16_f32 v0, v62, v1
	ds_write_b16 v26, v0 offset:27648
	v_cvt_pk_bf16_f32 v0, v58, v1
	ds_write_b16 v27, v0 offset:28224
	v_cvt_pk_bf16_f32 v0, v63, v1
	ds_write_b16 v26, v0 offset:27792
	v_cvt_pk_bf16_f32 v0, v59, v1
	ds_write_b16 v27, v0 offset:28368
	v_cvt_pk_bf16_f32 v0, v64, v1
	ds_write_b16 v26, v0 offset:27936
	v_cvt_pk_bf16_f32 v0, v60, v1
	ds_write_b16 v27, v0 offset:28512
	v_cvt_pk_bf16_f32 v0, v65, v1
	ds_write_b16 v26, v0 offset:28080
	v_cvt_pk_bf16_f32 v0, v61, v1
	ds_write_b16 v27, v0 offset:28656
	v_add_u32_e32 v0, s0, v3
	s_waitcnt lgkmcnt(0)
	s_barrier
	ds_read_b128 v[34:37], v33
	v_lshrrev_b32_e32 v0, 8, v0
	v_mov_b32_e32 v38, s1
	s_movk_i32 s1, 0x58
	v_mad_i32_i24 v24, v0, s1, v38
	v_ashrrev_i32_e32 v25, 31, v24
	v_lshlrev_b64 v[24:25], 15, v[24:25]
	v_lshl_add_u64 v[24:25], v[4:5], 0, v[24:25]
	v_add_u32_e32 v0, s0, v30
	s_waitcnt lgkmcnt(0)
	global_store_dwordx4 v[24:25], v[34:37], off
	ds_read_b128 v[34:37], v33 offset:9216
	v_lshrrev_b32_e32 v0, 8, v0
	v_mad_i32_i24 v24, v0, s1, v38
	v_ashrrev_i32_e32 v25, 31, v24
	v_lshlrev_b64 v[24:25], 15, v[24:25]
	v_lshl_add_u64 v[24:25], v[6:7], 0, v[24:25]
	v_add_u32_e32 v0, s0, v31
	s_waitcnt lgkmcnt(0)
	global_store_dwordx4 v[24:25], v[34:37], off
	ds_read_b128 v[34:37], v33 offset:18432
	v_lshrrev_b32_e32 v0, 8, v0
	v_mad_i32_i24 v24, v0, s1, v38
	v_ashrrev_i32_e32 v25, 31, v24
	v_lshlrev_b64 v[24:25], 15, v[24:25]
	v_lshl_add_u64 v[24:25], v[8:9], 0, v[24:25]
	v_add_u32_e32 v0, s0, v32
	s_waitcnt lgkmcnt(0)
	global_store_dwordx4 v[24:25], v[34:37], off
	ds_read_b128 v[34:37], v33 offset:27648
	v_lshrrev_b32_e32 v0, 8, v0
	v_mad_i32_i24 v24, v0, s1, v38
	v_ashrrev_i32_e32 v25, 31, v24
	v_lshlrev_b64 v[24:25], 15, v[24:25]
	v_lshl_add_u64 v[24:25], v[10:11], 0, v[24:25]
	s_waitcnt lgkmcnt(0)
	global_store_dwordx4 v[24:25], v[34:37], off
	s_barrier
	s_mov_b64 s[0:1], 0

; __device__ __forceinline__ bf16_t f2bf(float f) { return (bf16_t)(cvt_pk_bf16(f, 0.f) & 0xffffu); }
; __device__ __forceinline__ void cvt_tile(unsigned char* shm, int tid, const float* src, bf16_t* dst, int K, int N, int mode, const float* kscale, int ldd, int t) {
;     bf16_t* T = (bf16_t*)shm;
;     const int nnt = N / 256, nti = t % nnt, kt = t / nnt;
;     { const int k = tid >> 3, n8 = (tid & 7) * 8;
;       const float* s = src + (size_t)(kt * 64 + k) * N + nti * 256 + n8; const float ks = kscale ? kscale[kt * 64 + k] : 1.0f;
;       f32x4 v[8];
; #pragma unroll
;       for (int q = 0; q < 4; ++q) { v[2 * q] = *(const f32x4*)(s + q * 64); v[2 * q + 1] = *(const f32x4*)(s + q * 64 + 4); }
;       asm volatile("" ::: "memory");
; #pragma unroll
;       for (int q = 0; q < 4; ++q)
; #pragma unroll
;           for (int j = 0; j < 4; ++j) { T[(q * 64 + n8 + j) * 72 + k] = f2bf(v[2 * q][j] * ks); T[(q * 64 + n8 + 4 + j) * 72 + k] = f2bf(v[2 * q + 1][j] * ks); } }
;     __syncthreads();
; #pragma unroll
;     for (int q = 0; q < 4; ++q) { const int n = q * 64 + (tid >> 3), k8 = (tid & 7) * 8; const int nn = nti * 256 + n;
;       const int drow = mode == 0 ? nn : ((nn >> 7) * 256 + (nn & 127) + (mode == 2 ? 128 : 0));
;       *(u32x4*)(dst + ((size_t)((drow >> 8) * (K / 64) + kt) * 256 + (drow & 255)) * 64 + k8) = *(const u32x4*)(T + n * 72 + k8); }
;     __syncthreads();
; }
; __device__ __forceinline__ void cvt_ffn_tile(const Params& p, unsigned char* shm, int tid, bf16_t* W, int l, int sub, int t) {
;     const size_t wo = (size_t)(l * 2 + sub) * DM * DFF; const float* gk = p.in[2] + (l * 6 + (sub ? 4 : 0)) * DM;
;     if (t < 704) cvt_tile(shm, tid, p.in[26] + wo, W + W_13, DM, DFF, 1, gk, LDX, t);
;     else if (t < 1408) cvt_tile(shm, tid, p.in[27] + wo, W + W_13, DM, DFF, 2, gk, LDX, t - 704);
.LBB0_764:
	v_mov_b64_e32 v[34:35], s[42:43]
	s_movk_i32 s3, 0x5800
	v_mad_i64_i32 v[34:35], s[4:5], v24, s3, v[34:35]
	s_mul_i32 s3, s0, 22
	s_sub_i32 s1, s1, s3
	s_lshl_b32 s1, s1, 8
	s_and_b32 s1, s1, 0xff00
	s_lshl_b32 s48, s1, 2
	v_lshl_add_u64 v[34:35], v[34:35], 0, s[48:49]
	v_lshlrev_b32_e32 v0, 2, v2
	v_lshl_add_u64 v[62:63], v[34:35], 0, v[0:1]
	global_load_dwordx4 v[34:37], v[62:63], off nt
	global_load_dwordx4 v[38:41], v[62:63], off offset:16 nt
	global_load_dwordx4 v[42:45], v[62:63], off offset:256 nt
	global_load_dwordx4 v[46:49], v[62:63], off offset:272 nt
	global_load_dwordx4 v[50:53], v[62:63], off offset:512 nt
	global_load_dwordx4 v[54:57], v[62:63], off offset:528 nt
	global_load_dwordx4 v[58:61], v[62:63], off offset:768 nt
	s_nop 0
	global_load_dwordx4 v[62:65], v[62:63], off offset:784 nt
	s_movk_i32 s3, 0x4000
	s_waitcnt vmcnt(7)
	v_mul_f32_e32 v0, v25, v34
	s_waitcnt vmcnt(6)
	v_mul_f32_e32 v24, v25, v38
	v_mul_f32_e32 v33, v25, v35
	v_mul_f32_e32 v34, v25, v39
	v_mul_f32_e32 v35, v25, v36
	v_mul_f32_e32 v36, v25, v40
	v_mul_f32_e32 v37, v25, v37
	v_mul_f32_e32 v38, v25, v41
	s_waitcnt vmcnt(5)
	v_mul_f32_e32 v39, v25, v42
	s_waitcnt vmcnt(4)
	v_mul_f32_e32 v40, v25, v46
	v_mul_f32_e32 v41, v25, v43
	v_mul_f32_e32 v42, v25, v47
	v_mul_f32_e32 v43, v25, v44
	v_mul_f32_e32 v44, v25, v48
	v_mul_f32_e32 v45, v25, v45
	v_mul_f32_e32 v46, v25, v49
	s_waitcnt vmcnt(3)
	v_mul_f32_e32 v47, v25, v50
	s_waitcnt vmcnt(2)
	v_mul_f32_e32 v48, v25, v54
	v_mul_f32_e32 v49, v25, v51
	v_mul_f32_e32 v50, v25, v55
	v_mul_f32_e32 v51, v25, v52
	v_mul_f32_e32 v52, v25, v56
	v_mul_f32_e32 v53, v25, v53
	v_cvt_pk_bf16_f32 v0, v0, v1
	v_mul_f32_e32 v54, v25, v57
	v_cvt_pk_bf16_f32 v24, v24, v1
	v_cvt_pk_bf16_f32 v33, v33, v1
	v_cvt_pk_bf16_f32 v34, v34, v1
	v_cvt_pk_bf16_f32 v35, v35, v1
	v_cvt_pk_bf16_f32 v36, v36, v1
	v_cvt_pk_bf16_f32 v37, v37, v1
	v_cvt_pk_bf16_f32 v38, v38, v1
	v_cvt_pk_bf16_f32 v39, v39, v1
	v_cvt_pk_bf16_f32 v40, v40, v1
	v_cvt_pk_bf16_f32 v41, v41, v1
	v_cvt_pk_bf16_f32 v42, v42, v1
	v_cvt_pk_bf16_f32 v43, v43, v1
	v_cvt_pk_bf16_f32 v44, v44, v1
	v_cvt_pk_bf16_f32 v45, v45, v1
	v_cvt_pk_bf16_f32 v46, v46, v1
	v_cvt_pk_bf16_f32 v47, v47, v1
	v_cvt_pk_bf16_f32 v48, v48, v1
	v_cvt_pk_bf16_f32 v49, v49, v1
	v_cvt_pk_bf16_f32 v50, v50, v1
	v_cvt_pk_bf16_f32 v51, v51, v1
	v_cvt_pk_bf16_f32 v52, v52, v1
	v_cvt_pk_bf16_f32 v53, v53, v1
	ds_write_b16 v26, v0
	ds_write_b16 v27, v24 offset:576
	ds_write_b16 v26, v33 offset:144
	ds_write_b16 v27, v34 offset:720
	ds_write_b16 v26, v35 offset:288
	ds_write_b16 v27, v36 offset:864
	ds_write_b16 v26, v37 offset:432
	ds_write_b16 v27, v38 offset:1008
	ds_write_b16 v26, v39 offset:9216
	ds_write_b16 v27, v40 offset:9792
	ds_write_b16 v26, v41 offset:9360
	ds_write_b16 v27, v42 offset:9936
	ds_write_b16 v26, v43 offset:9504
	ds_write_b16 v27, v44 offset:10080
	ds_write_b16 v26, v45 offset:9648
	ds_write_b16 v27, v46 offset:10224
	ds_write_b16 v26, v47 offset:18432
	ds_write_b16 v27, v48 offset:19008
	ds_write_b16 v26, v49 offset:18576
	ds_write_b16 v27, v50 offset:19152
	ds_write_b16 v26, v51 offset:18720
	ds_write_b16 v27, v52 offset:19296
	ds_write_b16 v26, v53 offset:18864
	v_cvt_pk_bf16_f32 v0, v54, v1
	ds_write_b16 v27, v0 offset:19440
	s_waitcnt vmcnt(1)
	v_mul_f32_e32 v0, v25, v58
	v_cvt_pk_bf16_f32 v0, v0, v1
	ds_write_b16 v26, v0 offset:27648
	s_waitcnt vmcnt(0)
	v_mul_f32_e32 v0, v25, v62
	v_cvt_pk_bf16_f32 v0, v0, v1
	ds_write_b16 v27, v0 offset:28224
	v_mul_f32_e32 v0, v25, v59
	v_cvt_pk_bf16_f32 v0, v0, v1
	ds_write_b16 v26, v0 offset:27792
	v_mul_f32_e32 v0, v25, v63
	v_cvt_pk_bf16_f32 v0, v0, v1
	ds_write_b16 v27, v0 offset:28368
	v_mul_f32_e32 v0, v25, v60
	v_cvt_pk_bf16_f32 v0, v0, v1
	ds_write_b16 v26, v0 offset:27936
	v_mul_f32_e32 v0, v25, v64
	v_cvt_pk_bf16_f32 v0, v0, v1
	ds_write_b16 v27, v0 offset:28512
	v_mul_f32_e32 v0, v25, v61
	v_cvt_pk_bf16_f32 v0, v0, v1
	ds_write_b16 v26, v0 offset:28080
	v_mul_f32_e32 v0, v25, v65
	v_cvt_pk_bf16_f32 v0, v0, v1
	ds_write_b16 v27, v0 offset:28656
	v_add_u32_e32 v0, s1, v3
	v_ashrrev_i32_e32 v0, 2, v0
	v_and_b32_e32 v0, 0xffffffe0, v0
	v_add_u32_e32 v24, s0, v0
	v_add_u32_e32 v33, v28, v29
	v_ashrrev_i32_e32 v25, 31, v24
	s_waitcnt lgkmcnt(0)
	s_barrier
	ds_read_b128 v[34:37], v33
	ds_read_b128 v[38:41], v33 offset:9216
	v_lshlrev_b64 v[24:25], 15, v[24:25]
	v_lshl_add_u64 v[24:25], v[12:13], 0, v[24:25]
	v_lshlrev_b32_e32 v0, 1, v2
	v_lshl_add_u64 v[24:25], v[24:25], 0, v[0:1]
	v_add_co_u32_e32 v24, vcc, s3, v24
	s_nop 1
	v_addc_co_u32_e32 v25, vcc, 0, v25, vcc
	s_waitcnt lgkmcnt(1)
	global_store_dwordx4 v[24:25], v[34:37], off
	v_add_u32_e32 v24, s1, v30
	v_ashrrev_i32_e32 v24, 2, v24
	v_and_b32_e32 v24, 0xffffffe0, v24
	v_add_u32_e32 v24, s0, v24
	v_ashrrev_i32_e32 v25, 31, v24
	v_lshlrev_b64 v[24:25], 15, v[24:25]
	v_lshl_add_u64 v[24:25], v[14:15], 0, v[24:25]
	v_lshl_add_u64 v[24:25], v[24:25], 0, v[0:1]
	v_add_co_u32_e32 v24, vcc, s3, v24
	ds_read_b128 v[34:37], v33 offset:18432
	s_nop 0
	v_addc_co_u32_e32 v25, vcc, 0, v25, vcc
	s_waitcnt lgkmcnt(1)
	global_store_dwordx4 v[24:25], v[38:41], off
	v_add_u32_e32 v24, s1, v31
	v_ashrrev_i32_e32 v24, 2, v24
	v_and_b32_e32 v24, 0xffffffe0, v24
	v_add_u32_e32 v24, s0, v24
	v_ashrrev_i32_e32 v25, 31, v24
	v_lshlrev_b64 v[24:25], 15, v[24:25]
	v_lshl_add_u64 v[24:25], v[12:13], 0, v[24:25]
	v_lshl_add_u64 v[24:25], v[24:25], 0, v[0:1]
	v_add_co_u32_e32 v24, vcc, s3, v24
	ds_read_b128 v[38:41], v33 offset:27648
	s_nop 0
	v_addc_co_u32_e32 v25, vcc, 0, v25, vcc
	s_waitcnt lgkmcnt(1)
	global_store_dwordx4 v[24:25], v[34:37], off
	v_add_u32_e32 v24, s1, v32
	v_ashrrev_i32_e32 v24, 2, v24
	v_and_b32_e32 v24, 0xffffffe0, v24
	v_add_u32_e32 v24, s0, v24
	v_ashrrev_i32_e32 v25, 31, v24
	v_lshlrev_b64 v[24:25], 15, v[24:25]
	v_lshl_add_u64 v[24:25], v[16:17], 0, v[24:25]
	v_lshl_add_u64 v[24:25], v[24:25], 0, v[0:1]
	v_add_co_u32_e32 v24, vcc, 0x4000, v24
	s_nop 1
	v_addc_co_u32_e32 v25, vcc, 0, v25, vcc
	s_waitcnt lgkmcnt(0)
	global_store_dwordx4 v[24:25], v[38:41], off
	s_barrier

; __device__ __forceinline__ bf16_t f2bf(float f) { return (bf16_t)(cvt_pk_bf16(f, 0.f) & 0xffffu); }
; __device__ __forceinline__ void cvt_tile(unsigned char* shm, int tid, const float* src, bf16_t* dst, int K, int N, int mode, const float* kscale, int ldd, int t) {
;     bf16_t* T = (bf16_t*)shm;
;     const int nnt = N / 256, nti = t % nnt, kt = t / nnt;
;     { const int k = tid >> 3, n8 = (tid & 7) * 8;
;       const float* s = src + (size_t)(kt * 64 + k) * N + nti * 256 + n8; const float ks = kscale ? kscale[kt * 64 + k] : 1.0f;
;       f32x4 v[8];
; #pragma unroll
;       for (int q = 0; q < 4; ++q) { v[2 * q] = *(const f32x4*)(s + q * 64); v[2 * q + 1] = *(const f32x4*)(s + q * 64 + 4); }
;       asm volatile("" ::: "memory");
; #pragma unroll
;       for (int q = 0; q < 4; ++q)
; #pragma unroll
;           for (int j = 0; j < 4; ++j) { T[(q * 64 + n8 + j) * 72 + k] = f2bf(v[2 * q][j] * ks); T[(q * 64 + n8 + 4 + j) * 72 + k] = f2bf(v[2 * q + 1][j] * ks); } }
;     __syncthreads();
; #pragma unroll
;     for (int q = 0; q < 4; ++q) { const int n = q * 64 + (tid >> 3), k8 = (tid & 7) * 8; const int nn = nti * 256 + n;
;       const int drow = mode == 0 ? nn : ((nn >> 7) * 256 + (nn & 127) + (mode == 2 ? 128 : 0));
;       *(u32x4*)(dst + ((size_t)((drow >> 8) * (K / 64) + kt) * 256 + (drow & 255)) * 64 + k8) = *(const u32x4*)(T + n * 72 + k8); }
;     __syncthreads();
; }
; __device__ __forceinline__ void cvt_ffn_tile(const Params& p, unsigned char* shm, int tid, bf16_t* W, int l, int sub, int t) {
;     const size_t wo = (size_t)(l * 2 + sub) * DM * DFF; const float* gk = p.in[2] + (l * 6 + (sub ? 4 : 0)) * DM;
;     if (t < 704) cvt_tile(shm, tid, p.in[26] + wo, W + W_13, DM, DFF, 1, gk, LDX, t);
;     else if (t < 1408) cvt_tile(shm, tid, p.in[27] + wo, W + W_13, DM, DFF, 2, gk, LDX, t - 704);
;     else cvt_tile(shm, tid, p.in[28] + wo, W + W_2, DFF, DM, 0, nullptr, DFF, t - 1408);
.LBB0_951:
	s_or_b64 exec, exec, s[0:1]
	s_mov_b64 s[0:1], src_shared_base
	s_add_i32 s0, 0, 0x20080
	s_cmp_lg_u32 s0, -1
	s_cselect_b32 s0, s0, 0
	s_cselect_b32 s1, s1, 0
	v_mov_b32_e32 v24, s0
	v_mov_b32_e32 v25, s1
	s_waitcnt lgkmcnt(0)
	s_barrier
	ds_read_b32 v0, v24
	s_mov_b64 s[0:1], -1
	s_waitcnt lgkmcnt(0)
	s_barrier
	v_readfirstlane_b32 s2, v0
	s_cmpk_gt_i32 s2, 0x83f
	s_cbranch_scc1 .LBB0_946
	s_cmpk_gt_i32 s2, 0x2bf
	s_cbranch_scc0 .LBB0_961
	s_cmpk_gt_u32 s2, 0x57f
	s_cbranch_scc0 .LBB0_955
	s_add_i32 s0, s2, 0xfa80
	s_bfe_u32 s1, s0, 0xd0003
	v_lshl_add_u32 v24, s1, 6, v3
	v_ashrrev_i32_e32 v25, 31, v24
	v_readlane_b32 s4, v252, 37
	s_lshl_b32 s0, s2, 8
	v_lshlrev_b64 v[24:25], 13, v[24:25]
	v_readlane_b32 s5, v252, 38
	s_and_b32 s0, s0, 0x700
	s_lshl_b32 s48, s0, 2
	v_lshl_add_u64 v[24:25], s[4:5], 0, v[24:25]
	v_lshl_add_u64 v[24:25], v[24:25], 0, s[48:49]
	v_lshlrev_b32_e32 v0, 2, v2
	v_lshl_add_u64 v[24:25], v[24:25], 0, v[0:1]
	global_load_dwordx4 v[34:37], v[24:25], off offset:16 nt
	global_load_dwordx4 v[38:41], v[24:25], off nt
	global_load_dwordx4 v[42:45], v[24:25], off offset:272 nt
	global_load_dwordx4 v[46:49], v[24:25], off offset:256 nt
	global_load_dwordx4 v[50:53], v[24:25], off offset:528 nt
	global_load_dwordx4 v[54:57], v[24:25], off offset:512 nt
	global_load_dwordx4 v[58:61], v[24:25], off offset:784 nt
	global_load_dwordx4 v[62:65], v[24:25], off offset:768 nt
	v_add_u32_e32 v33, v28, v29
	s_waitcnt vmcnt(6)
	v_cvt_pk_bf16_f32 v0, v38, v1
	ds_write_b16 v26, v0
	v_cvt_pk_bf16_f32 v0, v34, v1
	ds_write_b16 v27, v0 offset:576
	v_cvt_pk_bf16_f32 v0, v39, v1
	ds_write_b16 v26, v0 offset:144
	v_cvt_pk_bf16_f32 v0, v35, v1
	ds_write_b16 v27, v0 offset:720
	v_cvt_pk_bf16_f32 v0, v40, v1
	ds_write_b16 v26, v0 offset:288
	v_cvt_pk_bf16_f32 v0, v36, v1
	ds_write_b16 v27, v0 offset:864
	v_cvt_pk_bf16_f32 v0, v41, v1
	ds_write_b16 v26, v0 offset:432
	v_cvt_pk_bf16_f32 v0, v37, v1
	ds_write_b16 v27, v0 offset:1008
	s_waitcnt vmcnt(4)
	v_cvt_pk_bf16_f32 v0, v46, v1
	ds_write_b16 v26, v0 offset:9216
	v_cvt_pk_bf16_f32 v0, v42, v1
	ds_write_b16 v27, v0 offset:9792
	v_cvt_pk_bf16_f32 v0, v47, v1
	ds_write_b16 v26, v0 offset:9360
	v_cvt_pk_bf16_f32 v0, v43, v1
	ds_write_b16 v27, v0 offset:9936
	v_cvt_pk_bf16_f32 v0, v48, v1
	ds_write_b16 v26, v0 offset:9504
	v_cvt_pk_bf16_f32 v0, v44, v1
	ds_write_b16 v27, v0 offset:10080
	v_cvt_pk_bf16_f32 v0, v49, v1
	ds_write_b16 v26, v0 offset:9648
	v_cvt_pk_bf16_f32 v0, v45, v1
	ds_write_b16 v27, v0 offset:10224
	s_waitcnt vmcnt(2)
	v_cvt_pk_bf16_f32 v0, v54, v1
	ds_write_b16 v26, v0 offset:18432
	v_cvt_pk_bf16_f32 v0, v50, v1
	ds_write_b16 v27, v0 offset:19008
	v_cvt_pk_bf16_f32 v0, v55, v1
	ds_write_b16 v26, v0 offset:18576
	v_cvt_pk_bf16_f32 v0, v51, v1
	ds_write_b16 v27, v0 offset:19152
	v_cvt_pk_bf16_f32 v0, v56, v1
	ds_write_b16 v26, v0 offset:18720
	v_cvt_pk_bf16_f32 v0, v52, v1
	ds_write_b16 v27, v0 offset:19296
	v_cvt_pk_bf16_f32 v0, v57, v1
	ds_write_b16 v26, v0 offset:18864
	v_cvt_pk_bf16_f32 v0, v53, v1
	ds_write_b16 v27, v0 offset:19440
	s_waitcnt vmcnt(0)
	v_cvt_pk_bf16_f32 v0, v62, v1
	ds_write_b16 v26, v0 offset:27648
	v_cvt_pk_bf16_f32 v0, v58, v1
	ds_write_b16 v27, v0 offset:28224
	v_cvt_pk_bf16_f32 v0, v63, v1
	ds_write_b16 v26, v0 offset:27792
	v_cvt_pk_bf16_f32 v0, v59, v1
	ds_write_b16 v27, v0 offset:28368
	v_cvt_pk_bf16_f32 v0, v64, v1
	ds_write_b16 v26, v0 offset:27936
	v_cvt_pk_bf16_f32 v0, v60, v1
	ds_write_b16 v27, v0 offset:28512
	v_cvt_pk_bf16_f32 v0, v65, v1
	ds_write_b16 v26, v0 offset:28080
	v_cvt_pk_bf16_f32 v0, v61, v1
	ds_write_b16 v27, v0 offset:28656
	v_add_u32_e32 v0, s0, v3
	s_waitcnt lgkmcnt(0)
	s_barrier
	ds_read_b128 v[34:37], v33
	v_lshrrev_b32_e32 v0, 8, v0
	v_mov_b32_e32 v38, s1
	s_movk_i32 s1, 0x58
	v_mad_i32_i24 v24, v0, s1, v38
	v_ashrrev_i32_e32 v25, 31, v24
	v_lshlrev_b64 v[24:25], 15, v[24:25]
	v_lshl_add_u64 v[24:25], v[4:5], 0, v[24:25]
	v_add_u32_e32 v0, s0, v30
	s_waitcnt lgkmcnt(0)
	global_store_dwordx4 v[24:25], v[34:37], off
	ds_read_b128 v[34:37], v33 offset:9216
	v_lshrrev_b32_e32 v0, 8, v0
	v_mad_i32_i24 v24, v0, s1, v38
	v_ashrrev_i32_e32 v25, 31, v24
	v_lshlrev_b64 v[24:25], 15, v[24:25]
	v_lshl_add_u64 v[24:25], v[6:7], 0, v[24:25]
	v_add_u32_e32 v0, s0, v31
	s_waitcnt lgkmcnt(0)
	global_store_dwordx4 v[24:25], v[34:37], off
	ds_read_b128 v[34:37], v33 offset:18432
	v_lshrrev_b32_e32 v0, 8, v0
	v_mad_i32_i24 v24, v0, s1, v38
	v_ashrrev_i32_e32 v25, 31, v24
	v_lshlrev_b64 v[24:25], 15, v[24:25]
	v_lshl_add_u64 v[24:25], v[8:9], 0, v[24:25]
	v_add_u32_e32 v0, s0, v32
	s_waitcnt lgkmcnt(0)
	global_store_dwordx4 v[24:25], v[34:37], off
	ds_read_b128 v[34:37], v33 offset:27648
	v_lshrrev_b32_e32 v0, 8, v0
	v_mad_i32_i24 v24, v0, s1, v38
	v_ashrrev_i32_e32 v25, 31, v24
	v_lshlrev_b64 v[24:25], 15, v[24:25]
	v_lshl_add_u64 v[24:25], v[10:11], 0, v[24:25]
	s_waitcnt lgkmcnt(0)
	global_store_dwordx4 v[24:25], v[34:37], off
	s_barrier
	s_mov_b64 s[0:1], 0

; __device__ __forceinline__ bf16_t f2bf(float f) { return (bf16_t)(cvt_pk_bf16(f, 0.f) & 0xffffu); }
; __device__ __forceinline__ void cvt_tile(unsigned char* shm, int tid, const float* src, bf16_t* dst, int K, int N, int mode, const float* kscale, int ldd, int t) {
;     bf16_t* T = (bf16_t*)shm;
;     const int nnt = N / 256, nti = t % nnt, kt = t / nnt;
;     { const int k = tid >> 3, n8 = (tid & 7) * 8;
;       const float* s = src + (size_t)(kt * 64 + k) * N + nti * 256 + n8; const float ks = kscale ? kscale[kt * 64 + k] : 1.0f;
;       f32x4 v[8];
; #pragma unroll
;       for (int q = 0; q < 4; ++q) { v[2 * q] = *(const f32x4*)(s + q * 64); v[2 * q + 1] = *(const f32x4*)(s + q * 64 + 4); }
;       asm volatile("" ::: "memory");
; #pragma unroll
;       for (int q = 0; q < 4; ++q)
; #pragma unroll
;           for (int j = 0; j < 4; ++j) { T[(q * 64 + n8 + j) * 72 + k] = f2bf(v[2 * q][j] * ks); T[(q * 64 + n8 + 4 + j) * 72 + k] = f2bf(v[2 * q + 1][j] * ks); } }
;     __syncthreads();
; #pragma unroll
;     for (int q = 0; q < 4; ++q) { const int n = q * 64 + (tid >> 3), k8 = (tid & 7) * 8; const int nn = nti * 256 + n;
;       const int drow = mode == 0 ? nn : ((nn >> 7) * 256 + (nn & 127) + (mode == 2 ? 128 : 0));
;       *(u32x4*)(dst + ((size_t)((drow >> 8) * (K / 64) + kt) * 256 + (drow & 255)) * 64 + k8) = *(const u32x4*)(T + n * 72 + k8); }
;     __syncthreads();
; }
; __device__ __forceinline__ void cvt_ffn_tile(const Params& p, unsigned char* shm, int tid, bf16_t* W, int l, int sub, int t) {
;     const size_t wo = (size_t)(l * 2 + sub) * DM * DFF; const float* gk = p.in[2] + (l * 6 + (sub ? 4 : 0)) * DM;
;     if (t < 704) cvt_tile(shm, tid, p.in[26] + wo, W + W_13, DM, DFF, 1, gk, LDX, t);
;     else if (t < 1408) cvt_tile(shm, tid, p.in[27] + wo, W + W_13, DM, DFF, 2, gk, LDX, t - 704);
.LBB0_959:
	v_readlane_b32 s4, v252, 39
	v_readlane_b32 s5, v252, 40
	s_movk_i32 s3, 0x5800
	v_lshlrev_b32_e32 v0, 2, v2
	v_mov_b64_e32 v[34:35], s[4:5]
	v_mad_i64_i32 v[34:35], s[4:5], v24, s3, v[34:35]
	s_mul_i32 s3, s0, 22
	s_sub_i32 s1, s1, s3
	s_lshl_b32 s1, s1, 8
	s_and_b32 s1, s1, 0xff00
	s_lshl_b32 s48, s1, 2
	v_lshl_add_u64 v[34:35], v[34:35], 0, s[48:49]
	v_lshl_add_u64 v[62:63], v[34:35], 0, v[0:1]
	global_load_dwordx4 v[34:37], v[62:63], off nt
	global_load_dwordx4 v[38:41], v[62:63], off offset:16 nt
	global_load_dwordx4 v[42:45], v[62:63], off offset:256 nt
	global_load_dwordx4 v[46:49], v[62:63], off offset:272 nt
	global_load_dwordx4 v[50:53], v[62:63], off offset:512 nt
	global_load_dwordx4 v[54:57], v[62:63], off offset:528 nt
	global_load_dwordx4 v[58:61], v[62:63], off offset:768 nt
	s_nop 0
	global_load_dwordx4 v[62:65], v[62:63], off offset:784 nt
	s_movk_i32 s3, 0x4000
	s_waitcnt vmcnt(7)
	v_mul_f32_e32 v0, v25, v34
	s_waitcnt vmcnt(6)
	v_mul_f32_e32 v24, v25, v38
	v_mul_f32_e32 v33, v25, v35
	v_mul_f32_e32 v34, v25, v39
	v_mul_f32_e32 v35, v25, v36
	v_mul_f32_e32 v36, v25, v40
	v_mul_f32_e32 v37, v25, v37
	v_mul_f32_e32 v38, v25, v41
	s_waitcnt vmcnt(5)
	v_mul_f32_e32 v39, v25, v42
	s_waitcnt vmcnt(4)
	v_mul_f32_e32 v40, v25, v46
	v_mul_f32_e32 v41, v25, v43
	v_mul_f32_e32 v42, v25, v47
	v_mul_f32_e32 v43, v25, v44
	v_mul_f32_e32 v44, v25, v48
	v_mul_f32_e32 v45, v25, v45
	v_mul_f32_e32 v46, v25, v49
	s_waitcnt vmcnt(3)
	v_mul_f32_e32 v47, v25, v50
	s_waitcnt vmcnt(2)
	v_mul_f32_e32 v48, v25, v54
	v_mul_f32_e32 v49, v25, v51
	v_mul_f32_e32 v50, v25, v55
	v_mul_f32_e32 v51, v25, v52
	v_mul_f32_e32 v52, v25, v56
	v_mul_f32_e32 v53, v25, v53
	v_cvt_pk_bf16_f32 v0, v0, v1
	v_mul_f32_e32 v54, v25, v57
	v_cvt_pk_bf16_f32 v24, v24, v1
	v_cvt_pk_bf16_f32 v33, v33, v1
	v_cvt_pk_bf16_f32 v34, v34, v1
	v_cvt_pk_bf16_f32 v35, v35, v1
	v_cvt_pk_bf16_f32 v36, v36, v1
	v_cvt_pk_bf16_f32 v37, v37, v1
	v_cvt_pk_bf16_f32 v38, v38, v1
	v_cvt_pk_bf16_f32 v39, v39, v1
	v_cvt_pk_bf16_f32 v40, v40, v1
	v_cvt_pk_bf16_f32 v41, v41, v1
	v_cvt_pk_bf16_f32 v42, v42, v1
	v_cvt_pk_bf16_f32 v43, v43, v1
	v_cvt_pk_bf16_f32 v44, v44, v1
	v_cvt_pk_bf16_f32 v45, v45, v1
	v_cvt_pk_bf16_f32 v46, v46, v1
	v_cvt_pk_bf16_f32 v47, v47, v1
	v_cvt_pk_bf16_f32 v48, v48, v1
	v_cvt_pk_bf16_f32 v49, v49, v1
	v_cvt_pk_bf16_f32 v50, v50, v1
	v_cvt_pk_bf16_f32 v51, v51, v1
	v_cvt_pk_bf16_f32 v52, v52, v1
	v_cvt_pk_bf16_f32 v53, v53, v1
	ds_write_b16 v26, v0
	ds_write_b16 v27, v24 offset:576
	ds_write_b16 v26, v33 offset:144
	ds_write_b16 v27, v34 offset:720
	ds_write_b16 v26, v35 offset:288
	ds_write_b16 v27, v36 offset:864
	ds_write_b16 v26, v37 offset:432
	ds_write_b16 v27, v38 offset:1008
	ds_write_b16 v26, v39 offset:9216
	ds_write_b16 v27, v40 offset:9792
	ds_write_b16 v26, v41 offset:9360
	ds_write_b16 v27, v42 offset:9936
	ds_write_b16 v26, v43 offset:9504
	ds_write_b16 v27, v44 offset:10080
	ds_write_b16 v26, v45 offset:9648
	ds_write_b16 v27, v46 offset:10224
	ds_write_b16 v26, v47 offset:18432
	ds_write_b16 v27, v48 offset:19008
	ds_write_b16 v26, v49 offset:18576
	ds_write_b16 v27, v50 offset:19152
	ds_write_b16 v26, v51 offset:18720
	ds_write_b16 v27, v52 offset:19296
	ds_write_b16 v26, v53 offset:18864
	v_cvt_pk_bf16_f32 v0, v54, v1
	ds_write_b16 v27, v0 offset:19440
	s_waitcnt vmcnt(1)
	v_mul_f32_e32 v0, v25, v58
	v_cvt_pk_bf16_f32 v0, v0, v1
	ds_write_b16 v26, v0 offset:27648
	s_waitcnt vmcnt(0)
	v_mul_f32_e32 v0, v25, v62
	v_cvt_pk_bf16_f32 v0, v0, v1
	ds_write_b16 v27, v0 offset:28224
	v_mul_f32_e32 v0, v25, v59
	v_cvt_pk_bf16_f32 v0, v0, v1
	ds_write_b16 v26, v0 offset:27792
	v_mul_f32_e32 v0, v25, v63
	v_cvt_pk_bf16_f32 v0, v0, v1
	ds_write_b16 v27, v0 offset:28368
	v_mul_f32_e32 v0, v25, v60
	v_cvt_pk_bf16_f32 v0, v0, v1
	ds_write_b16 v26, v0 offset:27936
	v_mul_f32_e32 v0, v25, v64
	v_cvt_pk_bf16_f32 v0, v0, v1
	ds_write_b16 v27, v0 offset:28512
	v_mul_f32_e32 v0, v25, v61
	v_cvt_pk_bf16_f32 v0, v0, v1
	ds_write_b16 v26, v0 offset:28080
	v_mul_f32_e32 v0, v25, v65
	v_cvt_pk_bf16_f32 v0, v0, v1
	ds_write_b16 v27, v0 offset:28656
	v_add_u32_e32 v0, s1, v3
	v_ashrrev_i32_e32 v0, 2, v0
	v_and_b32_e32 v0, 0xffffffe0, v0
	v_add_u32_e32 v24, s0, v0
	v_add_u32_e32 v33, v28, v29
	v_ashrrev_i32_e32 v25, 31, v24
	s_waitcnt lgkmcnt(0)
	s_barrier
	ds_read_b128 v[34:37], v33
	ds_read_b128 v[38:41], v33 offset:9216
	v_lshlrev_b64 v[24:25], 15, v[24:25]
	v_lshl_add_u64 v[24:25], v[12:13], 0, v[24:25]
	v_lshlrev_b32_e32 v0, 1, v2
	v_lshl_add_u64 v[24:25], v[24:25], 0, v[0:1]
	v_add_co_u32_e32 v24, vcc, s3, v24
	s_nop 1
	v_addc_co_u32_e32 v25, vcc, 0, v25, vcc
	s_waitcnt lgkmcnt(1)
	global_store_dwordx4 v[24:25], v[34:37], off
	v_add_u32_e32 v24, s1, v30
	v_ashrrev_i32_e32 v24, 2, v24
	v_and_b32_e32 v24, 0xffffffe0, v24
	v_add_u32_e32 v24, s0, v24
	v_ashrrev_i32_e32 v25, 31, v24
	v_lshlrev_b64 v[24:25], 15, v[24:25]
	v_lshl_add_u64 v[24:25], v[14:15], 0, v[24:25]
	v_lshl_add_u64 v[24:25], v[24:25], 0, v[0:1]
	v_add_co_u32_e32 v24, vcc, s3, v24
	ds_read_b128 v[34:37], v33 offset:18432
	s_nop 0
	v_addc_co_u32_e32 v25, vcc, 0, v25, vcc
	s_waitcnt lgkmcnt(1)
	global_store_dwordx4 v[24:25], v[38:41], off
	v_add_u32_e32 v24, s1, v31
	v_ashrrev_i32_e32 v24, 2, v24
	v_and_b32_e32 v24, 0xffffffe0, v24
	v_add_u32_e32 v24, s0, v24
	v_ashrrev_i32_e32 v25, 31, v24
	v_lshlrev_b64 v[24:25], 15, v[24:25]
	v_lshl_add_u64 v[24:25], v[12:13], 0, v[24:25]
	v_lshl_add_u64 v[24:25], v[24:25], 0, v[0:1]
	v_add_co_u32_e32 v24, vcc, s3, v24
	ds_read_b128 v[38:41], v33 offset:27648
	s_nop 0
	v_addc_co_u32_e32 v25, vcc, 0, v25, vcc
	s_waitcnt lgkmcnt(1)
	global_store_dwordx4 v[24:25], v[34:37], off
	v_add_u32_e32 v24, s1, v32
	v_ashrrev_i32_e32 v24, 2, v24
	v_and_b32_e32 v24, 0xffffffe0, v24
	v_add_u32_e32 v24, s0, v24
	v_ashrrev_i32_e32 v25, 31, v24
	v_lshlrev_b64 v[24:25], 15, v[24:25]
	v_lshl_add_u64 v[24:25], v[16:17], 0, v[24:25]
	v_lshl_add_u64 v[24:25], v[24:25], 0, v[0:1]
	v_add_co_u32_e32 v24, vcc, 0x4000, v24
	s_nop 1
	v_addc_co_u32_e32 v25, vcc, 0, v25, vcc
	s_waitcnt lgkmcnt(0)
	global_store_dwordx4 v[24:25], v[38:41], off
	s_barrier

; __device__ __forceinline__ bf16_t f2bf(float f) { return (bf16_t)(cvt_pk_bf16(f, 0.f) & 0xffffu); }
; __device__ __forceinline__ void cvt_tile(unsigned char* shm, int tid, const float* src, bf16_t* dst, int K, int N, int mode, const float* kscale, int ldd, int t) {
;     bf16_t* T = (bf16_t*)shm;
;     const int nnt = N / 256, nti = t % nnt, kt = t / nnt;
;     { const int k = tid >> 3, n8 = (tid & 7) * 8;
;       const float* s = src + (size_t)(kt * 64 + k) * N + nti * 256 + n8; const float ks = kscale ? kscale[kt * 64 + k] : 1.0f;
;       f32x4 v[8];
; #pragma unroll
;       for (int q = 0; q < 4; ++q) { v[2 * q] = *(const f32x4*)(s + q * 64); v[2 * q + 1] = *(const f32x4*)(s + q * 64 + 4); }
;       asm volatile("" ::: "memory");
; #pragma unroll
;       for (int q = 0; q < 4; ++q)
; #pragma unroll
;           for (int j = 0; j < 4; ++j) { T[(q * 64 + n8 + j) * 72 + k] = f2bf(v[2 * q][j] * ks); T[(q * 64 + n8 + 4 + j) * 72 + k] = f2bf(v[2 * q + 1][j] * ks); } }
;     __syncthreads();
; #pragma unroll
;     for (int q = 0; q < 4; ++q) { const int n = q * 64 + (tid >> 3), k8 = (tid & 7) * 8; const int nn = nti * 256 + n;
;       const int drow = mode == 0 ? nn : ((nn >> 7) * 256 + (nn & 127) + (mode == 2 ? 128 : 0));
;       *(u32x4*)(dst + ((size_t)((drow >> 8) * (K / 64) + kt) * 256 + (drow & 255)) * 64 + k8) = *(const u32x4*)(T + n * 72 + k8); }
;     __syncthreads();
; }
; __device__ __forceinline__ void cvt_mixer_tile(const Params& p, unsigned char* shm, int tid, bf16_t* W, int l, int t) {
;     if (t < 1728) cvt_tile(shm, tid, p.in[3] + (size_t)l * DM * 13824, W + W_IN, DM, 13824, 0, p.in[2] + (l * 6 + 2) * DM, LDX, t);
;     else if (t < 1792) cvt_tile(shm, tid, p.in[19] + (size_t)l * 1024 * 1024, W + W_GLU, 1024, 1024, 0, nullptr, 1024, t - 1728);
;     else if (t < 1920) cvt_tile(shm, tid, p.in[22] + (size_t)l * 1024 * DM, W + W_BRL, 1024, DM, 0, nullptr, 1024, t - 1792);
;     else if (t < 2048) cvt_tile(shm, tid, p.in[23] + (size_t)l * 1024 * DM, W + W_BRS, 1024, DM, 0, nullptr, 1024, t - 1920);
;     else if (t < 2112) cvt_tile(shm, tid, p.in[24] + (size_t)l * 512 * DM, W + W_BRA, 512, DM, 0, nullptr, 512, t - 2048);
;     else cvt_tile(shm, tid, p.in[25] + (size_t)l * DM * DM, W + W_OUT, DM, DM, 0, nullptr, DM, t - 2112);
; }
.LBB0_973:
	s_or_b64 exec, exec, s[0:1]
	s_mov_b64 s[0:1], src_shared_base
	s_add_i32 s0, 0, 0x20080
	s_cmp_lg_u32 s0, -1
	s_cselect_b32 s0, s0, 0
	s_cselect_b32 s1, s1, 0
	v_mov_b32_e32 v60, s0
	v_mov_b32_e32 v61, s1
	s_waitcnt lgkmcnt(0)
	s_barrier
	ds_read_b32 v0, v60
	s_mov_b64 s[0:1], -1
	s_waitcnt lgkmcnt(0)
	s_barrier
	v_readfirstlane_b32 s2, v0
	s_cmpk_gt_i32 s2, 0x93f
	s_cbranch_scc1 .LBB0_968
	s_cmpk_gt_i32 s2, 0x6bf
	s_cbranch_scc0 .LBB0_992
	s_cmpk_gt_u32 s2, 0x6ff
	s_cbranch_scc0 .LBB0_989
	s_cmpk_gt_u32 s2, 0x77f
	s_cbranch_scc0 .LBB0_986
	s_cmpk_gt_u32 s2, 0x7ff
	s_cbranch_scc0 .LBB0_983
	s_cmpk_gt_u32 s2, 0x83f
	s_cbranch_scc0 .LBB0_980
	s_add_i32 s1, s2, 0xc0
	s_bfe_u32 s0, s1, 0x50003
	v_lshl_add_u32 v60, s0, 6, v3
	v_ashrrev_i32_e32 v61, 31, v60
	s_lshl_b32 s0, s2, 8
	v_lshlrev_b64 v[60:61], 13, v[60:61]
	s_and_b32 s0, s0, 0x700
	v_lshl_add_u64 v[60:61], s[24:25], 0, v[60:61]
	s_lshl_b32 s48, s0, 2
	v_lshl_add_u64 v[60:61], v[60:61], 0, s[48:49]
	v_lshlrev_b32_e32 v0, 2, v2
	v_lshl_add_u64 v[88:89], v[60:61], 0, v[0:1]
	global_load_dwordx4 v[60:63], v[88:89], off nt
	global_load_dwordx4 v[64:67], v[88:89], off offset:16 nt
	global_load_dwordx4 v[68:71], v[88:89], off offset:256 nt
	global_load_dwordx4 v[72:75], v[88:89], off offset:272 nt
	global_load_dwordx4 v[76:79], v[88:89], off offset:512 nt
	global_load_dwordx4 v[80:83], v[88:89], off offset:528 nt
	global_load_dwordx4 v[84:87], v[88:89], off offset:768 nt
	s_nop 0
	global_load_dwordx4 v[88:91], v[88:89], off offset:784 nt
	s_lshr_b32 s1, s1, 3
	v_add_u32_e32 v0, s0, v3
	v_ashrrev_i32_e32 v0, 3, v0
	s_waitcnt vmcnt(7)
	v_cvt_pk_bf16_f32 v59, v60, v1
	s_waitcnt vmcnt(6)
	v_cvt_pk_bf16_f32 v60, v64, v1
	v_cvt_pk_bf16_f32 v61, v61, v1
	v_cvt_pk_bf16_f32 v64, v65, v1
	v_cvt_pk_bf16_f32 v62, v62, v1
	v_cvt_pk_bf16_f32 v65, v66, v1
	v_cvt_pk_bf16_f32 v63, v63, v1
	v_cvt_pk_bf16_f32 v66, v67, v1
	s_waitcnt vmcnt(5)
	v_cvt_pk_bf16_f32 v67, v68, v1
	s_waitcnt vmcnt(4)
	v_cvt_pk_bf16_f32 v68, v72, v1
	v_cvt_pk_bf16_f32 v69, v69, v1
	v_cvt_pk_bf16_f32 v72, v73, v1
	v_cvt_pk_bf16_f32 v70, v70, v1
	v_cvt_pk_bf16_f32 v73, v74, v1
	v_cvt_pk_bf16_f32 v71, v71, v1
	v_cvt_pk_bf16_f32 v74, v75, v1
	s_waitcnt vmcnt(3)
	v_cvt_pk_bf16_f32 v75, v76, v1
	s_waitcnt vmcnt(2)
	v_cvt_pk_bf16_f32 v76, v80, v1
	v_cvt_pk_bf16_f32 v77, v77, v1
	v_cvt_pk_bf16_f32 v80, v81, v1
	v_cvt_pk_bf16_f32 v78, v78, v1
	v_cvt_pk_bf16_f32 v81, v82, v1
	v_cvt_pk_bf16_f32 v79, v79, v1
	v_cvt_pk_bf16_f32 v82, v83, v1
	s_waitcnt vmcnt(1)
	v_cvt_pk_bf16_f32 v83, v84, v1
	s_waitcnt vmcnt(0)
	v_cvt_pk_bf16_f32 v84, v88, v1
	v_cvt_pk_bf16_f32 v85, v85, v1
	v_cvt_pk_bf16_f32 v88, v89, v1
	v_cvt_pk_bf16_f32 v86, v86, v1
	v_cvt_pk_bf16_f32 v89, v90, v1
	v_cvt_pk_bf16_f32 v87, v87, v1
	v_cvt_pk_bf16_f32 v90, v91, v1
	ds_write_b16 v52, v59
	ds_write_b16 v53, v60 offset:576
	ds_write_b16 v52, v61 offset:144
	ds_write_b16 v53, v64 offset:720
	ds_write_b16 v52, v62 offset:288
	ds_write_b16 v53, v65 offset:864
	ds_write_b16 v52, v63 offset:432
	ds_write_b16 v53, v66 offset:1008
	ds_write_b16 v52, v67 offset:9216
	ds_write_b16 v53, v68 offset:9792
	ds_write_b16 v52, v69 offset:9360
	ds_write_b16 v53, v72 offset:9936
	ds_write_b16 v52, v70 offset:9504
	ds_write_b16 v53, v73 offset:10080
	ds_write_b16 v52, v71 offset:9648
	ds_write_b16 v53, v74 offset:10224
	ds_write_b16 v52, v75 offset:18432
	ds_write_b16 v53, v76 offset:19008
	ds_write_b16 v52, v77 offset:18576
	ds_write_b16 v53, v80 offset:19152
	ds_write_b16 v52, v78 offset:18720
	ds_write_b16 v53, v81 offset:19296
	ds_write_b16 v52, v79 offset:18864
	ds_write_b16 v53, v82 offset:19440
	ds_write_b16 v52, v83 offset:27648
	ds_write_b16 v53, v84 offset:28224
	ds_write_b16 v52, v85 offset:27792
	ds_write_b16 v53, v88 offset:28368
	ds_write_b16 v52, v86 offset:27936
	ds_write_b16 v53, v89 offset:28512
	ds_write_b16 v52, v87 offset:28080
	ds_write_b16 v53, v90 offset:28656
	v_add_u32_e32 v59, v54, v55
	s_waitcnt lgkmcnt(0)
	s_barrier
	ds_read_b128 v[60:63], v59
	v_mov_b32_e32 v70, s1
	s_movk_i32 s1, 0xffe0
	v_bfi_b32 v64, s1, v0, v70
	v_ashrrev_i32_e32 v65, 31, v64
	v_lshlrev_b64 v[64:65], 15, v[64:65]
	v_add_u32_e32 v0, s0, v56
	v_lshl_add_u64 v[68:69], v[4:5], 0, v[64:65]
	ds_read_b128 v[64:67], v59 offset:9216
	v_ashrrev_i32_e32 v0, 3, v0
	s_waitcnt lgkmcnt(1)
	global_store_dwordx4 v[68:69], v[60:63], off
	s_nop 1
	v_bfi_b32 v60, s1, v0, v70
	v_ashrrev_i32_e32 v61, 31, v60
	v_lshlrev_b64 v[60:61], 15, v[60:61]
	v_lshl_add_u64 v[60:61], v[6:7], 0, v[60:61]
	v_add_u32_e32 v0, s0, v57
	s_waitcnt lgkmcnt(0)
	global_store_dwordx4 v[60:61], v[64:67], off
	ds_read_b128 v[60:63], v59 offset:18432
	v_ashrrev_i32_e32 v0, 3, v0
	v_bfi_b32 v64, s1, v0, v70
	v_ashrrev_i32_e32 v65, 31, v64
	v_lshlrev_b64 v[64:65], 15, v[64:65]
	v_add_u32_e32 v0, s0, v58
	v_lshl_add_u64 v[68:69], v[8:9], 0, v[64:65]
	ds_read_b128 v[64:67], v59 offset:27648
	v_ashrrev_i32_e32 v0, 3, v0
	s_waitcnt lgkmcnt(1)
	global_store_dwordx4 v[68:69], v[60:63], off
	s_nop 1
	v_bfi_b32 v60, s1, v0, v70
	v_ashrrev_i32_e32 v61, 31, v60
	v_lshlrev_b64 v[60:61], 15, v[60:61]
	v_lshl_add_u64 v[60:61], v[10:11], 0, v[60:61]
	s_waitcnt lgkmcnt(0)
	global_store_dwordx4 v[60:61], v[64:67], off
	s_barrier
	s_mov_b64 s[0:1], 0
; __device__ __forceinline__ bf16_t f2bf(float f) { return (bf16_t)(cvt_pk_bf16(f, 0.f) & 0xffffu); }
; __device__ __forceinline__ void cvt_tile(unsigned char* shm, int tid, const float* src, bf16_t* dst, int K, int N, int mode, const float* kscale, int ldd, int t) {
;     bf16_t* T = (bf16_t*)shm;
;     const int nnt = N / 256, nti = t % nnt, kt = t / nnt;
;     { const int k = tid >> 3, n8 = (tid & 7) * 8;
;       const float* s = src + (size_t)(kt * 64 + k) * N + nti * 256 + n8; const float ks = kscale ? kscale[kt * 64 + k] : 1.0f;
;       f32x4 v[8];
; #pragma unroll
;       for (int q = 0; q < 4; ++q) { v[2 * q] = *(const f32x4*)(s + q * 64); v[2 * q + 1] = *(const f32x4*)(s + q * 64 + 4); }
;       asm volatile("" ::: "memory");
; #pragma unroll
;       for (int q = 0; q < 4; ++q)
; #pragma unroll
;           for (int j = 0; j < 4; ++j) { T[(q * 64 + n8 + j) * 72 + k] = f2bf(v[2 * q][j] * ks); T[(q * 64 + n8 + 4 + j) * 72 + k] = f2bf(v[2 * q + 1][j] * ks); } }
;     __syncthreads();
; #pragma unroll
;     for (int q = 0; q < 4; ++q) { const int n = q * 64 + (tid >> 3), k8 = (tid & 7) * 8; const int nn = nti * 256 + n;
;       const int drow = mode == 0 ? nn : ((nn >> 7) * 256 + (nn & 127) + (mode == 2 ? 128 : 0));
;       *(u32x4*)(dst + ((size_t)((drow >> 8) * (K / 64) + kt) * 256 + (drow & 255)) * 64 + k8) = *(const u32x4*)(T + n * 72 + k8); }
;     __syncthreads();
; }
; __device__ __forceinline__ void cvt_mixer_tile(const Params& p, unsigned char* shm, int tid, bf16_t* W, int l, int t) {
;     ...
;     else if (t < 2112) cvt_tile(shm, tid, p.in[24] + (size_t)l * 512 * DM, W + W_BRA, 512, DM, 0, nullptr, 512, t - 2048);
.LBB0_980:
	s_andn2_b64 vcc, exec, s[0:1]
	s_cbranch_vccnz .LBB0_982
	s_bfe_u32 s0, s2, 0x50003
	v_lshl_add_u32 v60, s0, 6, v3
	v_ashrrev_i32_e32 v61, 31, v60
	s_lshl_b32 s1, s2, 8
	v_lshlrev_b64 v[60:61], 13, v[60:61]
	s_and_b32 s1, s1, 0x700
	v_lshl_add_u64 v[60:61], s[26:27], 0, v[60:61]
	s_lshl_b32 s48, s1, 2
	v_lshl_add_u64 v[60:61], v[60:61], 0, s[48:49]
	v_lshlrev_b32_e32 v0, 2, v2
	v_lshl_add_u64 v[88:89], v[60:61], 0, v[0:1]
	global_load_dwordx4 v[60:63], v[88:89], off offset:16 nt
	global_load_dwordx4 v[64:67], v[88:89], off nt
	global_load_dwordx4 v[68:71], v[88:89], off offset:272 nt
	global_load_dwordx4 v[72:75], v[88:89], off offset:256 nt
	global_load_dwordx4 v[76:79], v[88:89], off offset:528 nt
	global_load_dwordx4 v[80:83], v[88:89], off offset:512 nt
	global_load_dwordx4 v[84:87], v[88:89], off offset:784 nt
	s_nop 0
	global_load_dwordx4 v[88:91], v[88:89], off offset:768 nt
	v_add_u32_e32 v59, v54, v55
	s_waitcnt vmcnt(6)
	v_cvt_pk_bf16_f32 v0, v64, v1
	ds_write_b16 v52, v0
	v_cvt_pk_bf16_f32 v0, v60, v1
	ds_write_b16 v53, v0 offset:576
	v_cvt_pk_bf16_f32 v0, v65, v1
	ds_write_b16 v52, v0 offset:144
	v_cvt_pk_bf16_f32 v0, v61, v1
	ds_write_b16 v53, v0 offset:720
	v_cvt_pk_bf16_f32 v0, v66, v1
	ds_write_b16 v52, v0 offset:288
	v_cvt_pk_bf16_f32 v0, v62, v1
	ds_write_b16 v53, v0 offset:864
	v_cvt_pk_bf16_f32 v0, v67, v1
	ds_write_b16 v52, v0 offset:432
	v_cvt_pk_bf16_f32 v0, v63, v1
	ds_write_b16 v53, v0 offset:1008
	s_waitcnt vmcnt(4)
	v_cvt_pk_bf16_f32 v0, v72, v1
	ds_write_b16 v52, v0 offset:9216
	v_cvt_pk_bf16_f32 v0, v68, v1
	ds_write_b16 v53, v0 offset:9792
	v_cvt_pk_bf16_f32 v0, v73, v1
	ds_write_b16 v52, v0 offset:9360
	v_cvt_pk_bf16_f32 v0, v69, v1
	ds_write_b16 v53, v0 offset:9936
	v_cvt_pk_bf16_f32 v0, v74, v1
	ds_write_b16 v52, v0 offset:9504
	v_cvt_pk_bf16_f32 v0, v70, v1
	ds_write_b16 v53, v0 offset:10080
	v_cvt_pk_bf16_f32 v0, v75, v1
	ds_write_b16 v52, v0 offset:9648
	v_cvt_pk_bf16_f32 v0, v71, v1
	ds_write_b16 v53, v0 offset:10224
	s_waitcnt vmcnt(2)
	v_cvt_pk_bf16_f32 v0, v80, v1
	ds_write_b16 v52, v0 offset:18432
	v_cvt_pk_bf16_f32 v0, v76, v1
	ds_write_b16 v53, v0 offset:19008
	v_cvt_pk_bf16_f32 v0, v81, v1
	ds_write_b16 v52, v0 offset:18576
	v_cvt_pk_bf16_f32 v0, v77, v1
	ds_write_b16 v53, v0 offset:19152
	v_cvt_pk_bf16_f32 v0, v82, v1
	ds_write_b16 v52, v0 offset:18720
	v_cvt_pk_bf16_f32 v0, v78, v1
	ds_write_b16 v53, v0 offset:19296
	v_cvt_pk_bf16_f32 v0, v83, v1
	ds_write_b16 v52, v0 offset:18864
	v_cvt_pk_bf16_f32 v0, v79, v1
	ds_write_b16 v53, v0 offset:19440
	s_waitcnt vmcnt(0)
	v_cvt_pk_bf16_f32 v0, v88, v1
	ds_write_b16 v52, v0 offset:27648
	v_cvt_pk_bf16_f32 v0, v84, v1
	ds_write_b16 v53, v0 offset:28224
	v_cvt_pk_bf16_f32 v0, v89, v1
	ds_write_b16 v52, v0 offset:27792
	v_cvt_pk_bf16_f32 v0, v85, v1
	ds_write_b16 v53, v0 offset:28368
	v_cvt_pk_bf16_f32 v0, v90, v1
	ds_write_b16 v52, v0 offset:27936
	v_cvt_pk_bf16_f32 v0, v86, v1
	ds_write_b16 v53, v0 offset:28512
	v_cvt_pk_bf16_f32 v0, v91, v1
	ds_write_b16 v52, v0 offset:28080
	v_cvt_pk_bf16_f32 v0, v87, v1
	ds_write_b16 v53, v0 offset:28656
	v_add_u32_e32 v0, s1, v3
	v_ashrrev_i32_e32 v0, 5, v0
	s_waitcnt lgkmcnt(0)
	s_barrier
	ds_read_b128 v[60:63], v59
	v_and_b32_e32 v0, -8, v0
	v_add_u32_e32 v64, s0, v0
	v_ashrrev_i32_e32 v65, 31, v64
	v_lshlrev_b64 v[64:65], 15, v[64:65]
	v_add_u32_e32 v0, s1, v56
	v_lshl_add_u64 v[64:65], v[12:13], 0, v[64:65]
	v_ashrrev_i32_e32 v0, 5, v0
	s_waitcnt lgkmcnt(0)
	global_store_dwordx4 v[64:65], v[60:63], off
	ds_read_b128 v[60:63], v59 offset:9216
	v_and_b32_e32 v0, -8, v0
	v_add_u32_e32 v64, s0, v0
	v_ashrrev_i32_e32 v65, 31, v64
	v_lshlrev_b64 v[64:65], 15, v[64:65]
	v_add_u32_e32 v0, s1, v57
	v_lshl_add_u64 v[64:65], v[14:15], 0, v[64:65]
	v_ashrrev_i32_e32 v0, 5, v0
	s_waitcnt lgkmcnt(0)
	global_store_dwordx4 v[64:65], v[60:63], off
	ds_read_b128 v[60:63], v59 offset:18432
	v_and_b32_e32 v0, -8, v0
	v_add_u32_e32 v64, s0, v0
	v_ashrrev_i32_e32 v65, 31, v64
	v_lshlrev_b64 v[64:65], 15, v[64:65]
	v_add_u32_e32 v0, s1, v58
	v_lshl_add_u64 v[64:65], v[16:17], 0, v[64:65]
	v_ashrrev_i32_e32 v0, 5, v0
	s_waitcnt lgkmcnt(0)
	global_store_dwordx4 v[64:65], v[60:63], off
	ds_read_b128 v[60:63], v59 offset:27648
	v_and_b32_e32 v0, -8, v0
	v_add_u32_e32 v64, s0, v0
	v_ashrrev_i32_e32 v65, 31, v64
	v_lshlrev_b64 v[64:65], 15, v[64:65]
	v_lshl_add_u64 v[64:65], v[18:19], 0, v[64:65]
	s_waitcnt lgkmcnt(0)
	global_store_dwordx4 v[64:65], v[60:63], off
	s_barrier

; __device__ __forceinline__ bf16_t f2bf(float f) { return (bf16_t)(cvt_pk_bf16(f, 0.f) & 0xffffu); }
; __device__ __forceinline__ void cvt_tile(unsigned char* shm, int tid, const float* src, bf16_t* dst, int K, int N, int mode, const float* kscale, int ldd, int t) {
;     bf16_t* T = (bf16_t*)shm;
;     const int nnt = N / 256, nti = t % nnt, kt = t / nnt;
;     { const int k = tid >> 3, n8 = (tid & 7) * 8;
;       const float* s = src + (size_t)(kt * 64 + k) * N + nti * 256 + n8; const float ks = kscale ? kscale[kt * 64 + k] : 1.0f;
;       f32x4 v[8];
; #pragma unroll
;       for (int q = 0; q < 4; ++q) { v[2 * q] = *(const f32x4*)(s + q * 64); v[2 * q + 1] = *(const f32x4*)(s + q * 64 + 4); }
;       asm volatile("" ::: "memory");
; #pragma unroll
;       for (int q = 0; q < 4; ++q)
; #pragma unroll
;           for (int j = 0; j < 4; ++j) { T[(q * 64 + n8 + j) * 72 + k] = f2bf(v[2 * q][j] * ks); T[(q * 64 + n8 + 4 + j) * 72 + k] = f2bf(v[2 * q + 1][j] * ks); } }
;     __syncthreads();
; #pragma unroll
;     for (int q = 0; q < 4; ++q) { const int n = q * 64 + (tid >> 3), k8 = (tid & 7) * 8; const int nn = nti * 256 + n;
;       const int drow = mode == 0 ? nn : ((nn >> 7) * 256 + (nn & 127) + (mode == 2 ? 128 : 0));
;       *(u32x4*)(dst + ((size_t)((drow >> 8) * (K / 64) + kt) * 256 + (drow & 255)) * 64 + k8) = *(const u32x4*)(T + n * 72 + k8); }
;     __syncthreads();
; }
; __device__ __forceinline__ void cvt_mixer_tile(const Params& p, unsigned char* shm, int tid, bf16_t* W, int l, int t) {
;     ...
;     else if (t < 2048) cvt_tile(shm, tid, p.in[23] + (size_t)l * 1024 * DM, W + W_BRS, 1024, DM, 0, nullptr, 1024, t - 1920);
.LBB0_983:
	s_andn2_b64 vcc, exec, s[0:1]
	s_cbranch_vccnz .LBB0_985
	s_bfe_u32 s0, s2, 0x50003
	s_xor_b32 s0, s0, 16
	v_lshl_add_u32 v60, s0, 6, v3
	v_ashrrev_i32_e32 v61, 31, v60
	s_lshl_b32 s1, s2, 8
	v_lshlrev_b64 v[60:61], 13, v[60:61]
	s_and_b32 s1, s1, 0x700
	v_lshl_add_u64 v[60:61], s[38:39], 0, v[60:61]
	s_lshl_b32 s48, s1, 2
	v_lshl_add_u64 v[60:61], v[60:61], 0, s[48:49]
	v_lshlrev_b32_e32 v0, 2, v2
	v_lshl_add_u64 v[88:89], v[60:61], 0, v[0:1]
	global_load_dwordx4 v[60:63], v[88:89], off offset:16 nt
	global_load_dwordx4 v[64:67], v[88:89], off nt
	global_load_dwordx4 v[68:71], v[88:89], off offset:272 nt
	global_load_dwordx4 v[72:75], v[88:89], off offset:256 nt
	global_load_dwordx4 v[76:79], v[88:89], off offset:528 nt
	global_load_dwordx4 v[80:83], v[88:89], off offset:512 nt
	global_load_dwordx4 v[84:87], v[88:89], off offset:784 nt
	s_nop 0
	global_load_dwordx4 v[88:91], v[88:89], off offset:768 nt
	v_add_u32_e32 v59, v54, v55
	s_waitcnt vmcnt(6)
	v_cvt_pk_bf16_f32 v0, v64, v1
	ds_write_b16 v52, v0
	v_cvt_pk_bf16_f32 v0, v60, v1
	ds_write_b16 v53, v0 offset:576
	v_cvt_pk_bf16_f32 v0, v65, v1
	ds_write_b16 v52, v0 offset:144
	v_cvt_pk_bf16_f32 v0, v61, v1
	ds_write_b16 v53, v0 offset:720
	v_cvt_pk_bf16_f32 v0, v66, v1
	ds_write_b16 v52, v0 offset:288
	v_cvt_pk_bf16_f32 v0, v62, v1
	ds_write_b16 v53, v0 offset:864
	v_cvt_pk_bf16_f32 v0, v67, v1
	ds_write_b16 v52, v0 offset:432
	v_cvt_pk_bf16_f32 v0, v63, v1
	ds_write_b16 v53, v0 offset:1008
	s_waitcnt vmcnt(4)
	v_cvt_pk_bf16_f32 v0, v72, v1
	ds_write_b16 v52, v0 offset:9216
	v_cvt_pk_bf16_f32 v0, v68, v1
	ds_write_b16 v53, v0 offset:9792
	v_cvt_pk_bf16_f32 v0, v73, v1
	ds_write_b16 v52, v0 offset:9360
	v_cvt_pk_bf16_f32 v0, v69, v1
	ds_write_b16 v53, v0 offset:9936
	v_cvt_pk_bf16_f32 v0, v74, v1
	ds_write_b16 v52, v0 offset:9504
	v_cvt_pk_bf16_f32 v0, v70, v1
	ds_write_b16 v53, v0 offset:10080
	v_cvt_pk_bf16_f32 v0, v75, v1
	ds_write_b16 v52, v0 offset:9648
	v_cvt_pk_bf16_f32 v0, v71, v1
	ds_write_b16 v53, v0 offset:10224
	s_waitcnt vmcnt(2)
	v_cvt_pk_bf16_f32 v0, v80, v1
	ds_write_b16 v52, v0 offset:18432
	v_cvt_pk_bf16_f32 v0, v76, v1
	ds_write_b16 v53, v0 offset:19008
	v_cvt_pk_bf16_f32 v0, v81, v1
	ds_write_b16 v52, v0 offset:18576
	v_cvt_pk_bf16_f32 v0, v77, v1
	ds_write_b16 v53, v0 offset:19152
	v_cvt_pk_bf16_f32 v0, v82, v1
	ds_write_b16 v52, v0 offset:18720
	v_cvt_pk_bf16_f32 v0, v78, v1
	ds_write_b16 v53, v0 offset:19296
	v_cvt_pk_bf16_f32 v0, v83, v1
	ds_write_b16 v52, v0 offset:18864
	v_cvt_pk_bf16_f32 v0, v79, v1
	ds_write_b16 v53, v0 offset:19440
	s_waitcnt vmcnt(0)
	v_cvt_pk_bf16_f32 v0, v88, v1
	ds_write_b16 v52, v0 offset:27648
	v_cvt_pk_bf16_f32 v0, v84, v1
	ds_write_b16 v53, v0 offset:28224
	v_cvt_pk_bf16_f32 v0, v89, v1
	ds_write_b16 v52, v0 offset:27792
	v_cvt_pk_bf16_f32 v0, v85, v1
	ds_write_b16 v53, v0 offset:28368
	v_cvt_pk_bf16_f32 v0, v90, v1
	ds_write_b16 v52, v0 offset:27936
	v_cvt_pk_bf16_f32 v0, v86, v1
	ds_write_b16 v53, v0 offset:28512
	v_cvt_pk_bf16_f32 v0, v91, v1
	ds_write_b16 v52, v0 offset:28080
	v_cvt_pk_bf16_f32 v0, v87, v1
	ds_write_b16 v53, v0 offset:28656
	v_add_u32_e32 v0, s1, v3
	v_ashrrev_i32_e32 v0, 4, v0
	s_waitcnt lgkmcnt(0)
	s_barrier
	ds_read_b128 v[60:63], v59
	v_and_b32_e32 v0, -16, v0
	v_add_u32_e32 v64, s0, v0
	v_ashrrev_i32_e32 v65, 31, v64
	v_lshlrev_b64 v[64:65], 15, v[64:65]
	v_add_u32_e32 v0, s1, v56
	v_lshl_add_u64 v[64:65], v[20:21], 0, v[64:65]
	v_ashrrev_i32_e32 v0, 4, v0
	s_waitcnt lgkmcnt(0)
	global_store_dwordx4 v[64:65], v[60:63], off
	ds_read_b128 v[60:63], v59 offset:9216
	v_and_b32_e32 v0, -16, v0
	v_add_u32_e32 v64, s0, v0
	v_ashrrev_i32_e32 v65, 31, v64
	v_lshlrev_b64 v[64:65], 15, v[64:65]
	v_add_u32_e32 v0, s1, v57
	v_lshl_add_u64 v[64:65], v[22:23], 0, v[64:65]
	v_ashrrev_i32_e32 v0, 4, v0
	s_waitcnt lgkmcnt(0)
	global_store_dwordx4 v[64:65], v[60:63], off
	ds_read_b128 v[60:63], v59 offset:18432
	v_and_b32_e32 v0, -16, v0
	v_add_u32_e32 v64, s0, v0
	v_ashrrev_i32_e32 v65, 31, v64
	v_lshlrev_b64 v[64:65], 15, v[64:65]
	v_add_u32_e32 v0, s1, v58
	v_lshl_add_u64 v[64:65], v[24:25], 0, v[64:65]
	v_ashrrev_i32_e32 v0, 4, v0
	s_waitcnt lgkmcnt(0)
	global_store_dwordx4 v[64:65], v[60:63], off
	ds_read_b128 v[60:63], v59 offset:27648
	v_and_b32_e32 v0, -16, v0
	v_add_u32_e32 v64, s0, v0
	v_ashrrev_i32_e32 v65, 31, v64
	v_lshlrev_b64 v[64:65], 15, v[64:65]
	v_lshl_add_u64 v[64:65], v[26:27], 0, v[64:65]
	s_waitcnt lgkmcnt(0)
	global_store_dwordx4 v[64:65], v[60:63], off
	s_barrier

; __device__ __forceinline__ bf16_t f2bf(float f) { return (bf16_t)(cvt_pk_bf16(f, 0.f) & 0xffffu); }
; __device__ __forceinline__ void cvt_tile(unsigned char* shm, int tid, const float* src, bf16_t* dst, int K, int N, int mode, const float* kscale, int ldd, int t) {
;     ...
;     { const int k = tid >> 3, n8 = (tid & 7) * 8;
;       const float* s = src + (size_t)(kt * 64 + k) * N + nti * 256 + n8; const float ks = kscale ? kscale[kt * 64 + k] : 1.0f;
;       f32x4 v[8];
; #pragma unroll
;       for (int q = 0; q < 4; ++q) { v[2 * q] = *(const f32x4*)(s + q * 64); v[2 * q + 1] = *(const f32x4*)(s + q * 64 + 4); }
;       asm volatile("" ::: "memory");
; #pragma unroll
;       for (int q = 0; q < 4; ++q)
; #pragma unroll
;           for (int j = 0; j < 4; ++j) { T[(q * 64 + n8 + j) * 72 + k] = f2bf(v[2 * q][j] * ks); T[(q * 64 + n8 + 4 + j) * 72 + k] = f2bf(v[2 * q + 1][j] * ks); } }
;     __syncthreads();
; #pragma unroll
;     for (int q = 0; q < 4; ++q) { const int n = q * 64 + (tid >> 3), k8 = (tid & 7) * 8; const int nn = nti * 256 + n;
;       const int drow = mode == 0 ? nn : ((nn >> 7) * 256 + (nn & 127) + (mode == 2 ? 128 : 0));
;       *(u32x4*)(dst + ((size_t)((drow >> 8) * (K / 64) + kt) * 256 + (drow & 255)) * 64 + k8) = *(const u32x4*)(T + n * 72 + k8); }
;     __syncthreads();
.LBB0_986:
	s_andn2_b64 vcc, exec, s[0:1]
	s_cbranch_vccnz .LBB0_988
	s_bfe_u32 s0, s2, 0x50003
	v_lshl_add_u32 v60, s0, 6, v3
	v_ashrrev_i32_e32 v61, 31, v60
	s_lshl_b32 s1, s2, 8
	v_lshlrev_b64 v[60:61], 13, v[60:61]
	s_and_b32 s1, s1, 0x700
	v_lshl_add_u64 v[60:61], s[42:43], 0, v[60:61]
	s_lshl_b32 s48, s1, 2
	v_lshl_add_u64 v[60:61], v[60:61], 0, s[48:49]
	v_lshlrev_b32_e32 v0, 2, v2
	v_lshl_add_u64 v[88:89], v[60:61], 0, v[0:1]
	global_load_dwordx4 v[60:63], v[88:89], off offset:16 nt
	global_load_dwordx4 v[64:67], v[88:89], off nt
	global_load_dwordx4 v[68:71], v[88:89], off offset:272 nt
	global_load_dwordx4 v[72:75], v[88:89], off offset:256 nt
	global_load_dwordx4 v[76:79], v[88:89], off offset:528 nt
	global_load_dwordx4 v[80:83], v[88:89], off offset:512 nt
	global_load_dwordx4 v[84:87], v[88:89], off offset:784 nt
	s_nop 0
	global_load_dwordx4 v[88:91], v[88:89], off offset:768 nt
	v_add_u32_e32 v59, v54, v55
	s_waitcnt vmcnt(6)
	v_cvt_pk_bf16_f32 v0, v64, v1
	ds_write_b16 v52, v0
	v_cvt_pk_bf16_f32 v0, v60, v1
	ds_write_b16 v53, v0 offset:576
	v_cvt_pk_bf16_f32 v0, v65, v1
	ds_write_b16 v52, v0 offset:144
	v_cvt_pk_bf16_f32 v0, v61, v1
	ds_write_b16 v53, v0 offset:720
	v_cvt_pk_bf16_f32 v0, v66, v1
	ds_write_b16 v52, v0 offset:288
	v_cvt_pk_bf16_f32 v0, v62, v1
	ds_write_b16 v53, v0 offset:864
	v_cvt_pk_bf16_f32 v0, v67, v1
	ds_write_b16 v52, v0 offset:432
	v_cvt_pk_bf16_f32 v0, v63, v1
	ds_write_b16 v53, v0 offset:1008
	s_waitcnt vmcnt(4)
	v_cvt_pk_bf16_f32 v0, v72, v1
	ds_write_b16 v52, v0 offset:9216
	v_cvt_pk_bf16_f32 v0, v68, v1
	ds_write_b16 v53, v0 offset:9792
	v_cvt_pk_bf16_f32 v0, v73, v1
	ds_write_b16 v52, v0 offset:9360
	v_cvt_pk_bf16_f32 v0, v69, v1
	ds_write_b16 v53, v0 offset:9936
	v_cvt_pk_bf16_f32 v0, v74, v1
	ds_write_b16 v52, v0 offset:9504
	v_cvt_pk_bf16_f32 v0, v70, v1
	ds_write_b16 v53, v0 offset:10080
	v_cvt_pk_bf16_f32 v0, v75, v1
	ds_write_b16 v52, v0 offset:9648
	v_cvt_pk_bf16_f32 v0, v71, v1
	ds_write_b16 v53, v0 offset:10224
	s_waitcnt vmcnt(2)
	v_cvt_pk_bf16_f32 v0, v80, v1
	ds_write_b16 v52, v0 offset:18432
	v_cvt_pk_bf16_f32 v0, v76, v1
	ds_write_b16 v53, v0 offset:19008
	v_cvt_pk_bf16_f32 v0, v81, v1
	ds_write_b16 v52, v0 offset:18576
	v_cvt_pk_bf16_f32 v0, v77, v1
	ds_write_b16 v53, v0 offset:19152
	v_cvt_pk_bf16_f32 v0, v82, v1
	ds_write_b16 v52, v0 offset:18720
	v_cvt_pk_bf16_f32 v0, v78, v1
	ds_write_b16 v53, v0 offset:19296
	v_cvt_pk_bf16_f32 v0, v83, v1
	ds_write_b16 v52, v0 offset:18864
	v_cvt_pk_bf16_f32 v0, v79, v1
	ds_write_b16 v53, v0 offset:19440
	s_waitcnt vmcnt(0)
	v_cvt_pk_bf16_f32 v0, v88, v1
	ds_write_b16 v52, v0 offset:27648
	v_cvt_pk_bf16_f32 v0, v84, v1
	ds_write_b16 v53, v0 offset:28224
	v_cvt_pk_bf16_f32 v0, v89, v1
	ds_write_b16 v52, v0 offset:27792
	v_cvt_pk_bf16_f32 v0, v85, v1
	ds_write_b16 v53, v0 offset:28368
	v_cvt_pk_bf16_f32 v0, v90, v1
	ds_write_b16 v52, v0 offset:27936
	v_cvt_pk_bf16_f32 v0, v86, v1
	ds_write_b16 v53, v0 offset:28512
	v_cvt_pk_bf16_f32 v0, v91, v1
	ds_write_b16 v52, v0 offset:28080
	v_cvt_pk_bf16_f32 v0, v87, v1
	ds_write_b16 v53, v0 offset:28656
	v_add_u32_e32 v0, s1, v3
	v_ashrrev_i32_e32 v0, 4, v0
	s_waitcnt lgkmcnt(0)
	s_barrier
	ds_read_b128 v[60:63], v59
	v_and_b32_e32 v0, -16, v0
	v_add_u32_e32 v64, s0, v0
	v_ashrrev_i32_e32 v65, 31, v64
	v_lshlrev_b64 v[64:65], 15, v[64:65]
	v_add_u32_e32 v0, s1, v56
	v_lshl_add_u64 v[64:65], v[28:29], 0, v[64:65]
	v_ashrrev_i32_e32 v0, 4, v0
	s_waitcnt lgkmcnt(0)
	global_store_dwordx4 v[64:65], v[60:63], off
	ds_read_b128 v[60:63], v59 offset:9216
	v_and_b32_e32 v0, -16, v0
	v_add_u32_e32 v64, s0, v0
	v_ashrrev_i32_e32 v65, 31, v64
	v_lshlrev_b64 v[64:65], 15, v[64:65]
	v_add_u32_e32 v0, s1, v57
	v_lshl_add_u64 v[64:65], v[30:31], 0, v[64:65]
	v_ashrrev_i32_e32 v0, 4, v0
	s_waitcnt lgkmcnt(0)
	global_store_dwordx4 v[64:65], v[60:63], off
	ds_read_b128 v[60:63], v59 offset:18432
	v_and_b32_e32 v0, -16, v0
	v_add_u32_e32 v64, s0, v0
	v_ashrrev_i32_e32 v65, 31, v64
	v_lshlrev_b64 v[64:65], 15, v[64:65]
	v_add_u32_e32 v0, s1, v58
	v_lshl_add_u64 v[64:65], v[32:33], 0, v[64:65]
	v_ashrrev_i32_e32 v0, 4, v0
	s_waitcnt lgkmcnt(0)
	global_store_dwordx4 v[64:65], v[60:63], off
	ds_read_b128 v[60:63], v59 offset:27648
	v_and_b32_e32 v0, -16, v0
	v_add_u32_e32 v64, s0, v0
	v_ashrrev_i32_e32 v65, 31, v64
	v_lshlrev_b64 v[64:65], 15, v[64:65]
	v_lshl_add_u64 v[64:65], v[34:35], 0, v[64:65]
	s_waitcnt lgkmcnt(0)
	global_store_dwordx4 v[64:65], v[60:63], off
	s_barrier

; __device__ __forceinline__ bf16_t f2bf(float f) { return (bf16_t)(cvt_pk_bf16(f, 0.f) & 0xffffu); }
; __device__ __forceinline__ void cvt_tile(unsigned char* shm, int tid, const float* src, bf16_t* dst, int K, int N, int mode, const float* kscale, int ldd, int t) {
;     ...
;     { const int k = tid >> 3, n8 = (tid & 7) * 8;
;       const float* s = src + (size_t)(kt * 64 + k) * N + nti * 256 + n8; const float ks = kscale ? kscale[kt * 64 + k] : 1.0f;
;       f32x4 v[8];
; #pragma unroll
;       for (int q = 0; q < 4; ++q) { v[2 * q] = *(const f32x4*)(s + q * 64); v[2 * q + 1] = *(const f32x4*)(s + q * 64 + 4); }
;       asm volatile("" ::: "memory");
; #pragma unroll
;       for (int q = 0; q < 4; ++q)
; #pragma unroll
;           for (int j = 0; j < 4; ++j) { T[(q * 64 + n8 + j) * 72 + k] = f2bf(v[2 * q][j] * ks); T[(q * 64 + n8 + 4 + j) * 72 + k] = f2bf(v[2 * q + 1][j] * ks); } }
;     __syncthreads();
; #pragma unroll
;     for (int q = 0; q < 4; ++q) { const int n = q * 64 + (tid >> 3), k8 = (tid & 7) * 8; const int nn = nti * 256 + n;
;       const int drow = mode == 0 ? nn : ((nn >> 7) * 256 + (nn & 127) + (mode == 2 ? 128 : 0));
;       *(u32x4*)(dst + ((size_t)((drow >> 8) * (K / 64) + kt) * 256 + (drow & 255)) * 64 + k8) = *(const u32x4*)(T + n * 72 + k8); }
;     __syncthreads();
.LBB0_989:
	s_andn2_b64 vcc, exec, s[0:1]
	s_cbranch_vccnz .LBB0_991
	s_add_i32 s0, s2, 64
	s_bfe_u32 s0, s0, 0x60002
	v_lshl_add_u32 v60, s0, 6, v3
	v_ashrrev_i32_e32 v61, 31, v60
	s_lshl_b32 s1, s2, 8
	v_lshlrev_b64 v[60:61], 12, v[60:61]
	s_and_b32 s1, s1, 0x300
	v_lshl_add_u64 v[60:61], s[50:51], 0, v[60:61]
	s_lshl_b32 s48, s1, 2
	v_lshl_add_u64 v[60:61], v[60:61], 0, s[48:49]
	v_lshlrev_b32_e32 v0, 2, v2
	v_lshl_add_u64 v[88:89], v[60:61], 0, v[0:1]
	global_load_dwordx4 v[60:63], v[88:89], off offset:16 nt
	global_load_dwordx4 v[64:67], v[88:89], off nt
	global_load_dwordx4 v[68:71], v[88:89], off offset:272 nt
	global_load_dwordx4 v[72:75], v[88:89], off offset:256 nt
	global_load_dwordx4 v[76:79], v[88:89], off offset:528 nt
	global_load_dwordx4 v[80:83], v[88:89], off offset:512 nt
	global_load_dwordx4 v[84:87], v[88:89], off offset:784 nt
	s_nop 0
	global_load_dwordx4 v[88:91], v[88:89], off offset:768 nt
	v_add_u32_e32 v59, v54, v55
	s_waitcnt vmcnt(6)
	v_cvt_pk_bf16_f32 v0, v64, v1
	ds_write_b16 v52, v0
	v_cvt_pk_bf16_f32 v0, v60, v1
	ds_write_b16 v53, v0 offset:576
	v_cvt_pk_bf16_f32 v0, v65, v1
	ds_write_b16 v52, v0 offset:144
	v_cvt_pk_bf16_f32 v0, v61, v1
	ds_write_b16 v53, v0 offset:720
	v_cvt_pk_bf16_f32 v0, v66, v1
	ds_write_b16 v52, v0 offset:288
	v_cvt_pk_bf16_f32 v0, v62, v1
	ds_write_b16 v53, v0 offset:864
	v_cvt_pk_bf16_f32 v0, v67, v1
	ds_write_b16 v52, v0 offset:432
	v_cvt_pk_bf16_f32 v0, v63, v1
	ds_write_b16 v53, v0 offset:1008
	s_waitcnt vmcnt(4)
	v_cvt_pk_bf16_f32 v0, v72, v1
	ds_write_b16 v52, v0 offset:9216
	v_cvt_pk_bf16_f32 v0, v68, v1
	ds_write_b16 v53, v0 offset:9792
	v_cvt_pk_bf16_f32 v0, v73, v1
	ds_write_b16 v52, v0 offset:9360
	v_cvt_pk_bf16_f32 v0, v69, v1
	ds_write_b16 v53, v0 offset:9936
	v_cvt_pk_bf16_f32 v0, v74, v1
	ds_write_b16 v52, v0 offset:9504
	v_cvt_pk_bf16_f32 v0, v70, v1
	ds_write_b16 v53, v0 offset:10080
	v_cvt_pk_bf16_f32 v0, v75, v1
	ds_write_b16 v52, v0 offset:9648
	v_cvt_pk_bf16_f32 v0, v71, v1
	ds_write_b16 v53, v0 offset:10224
	s_waitcnt vmcnt(2)
	v_cvt_pk_bf16_f32 v0, v80, v1
	ds_write_b16 v52, v0 offset:18432
	v_cvt_pk_bf16_f32 v0, v76, v1
	ds_write_b16 v53, v0 offset:19008
	v_cvt_pk_bf16_f32 v0, v81, v1
	ds_write_b16 v52, v0 offset:18576
	v_cvt_pk_bf16_f32 v0, v77, v1
	ds_write_b16 v53, v0 offset:19152
	v_cvt_pk_bf16_f32 v0, v82, v1
	ds_write_b16 v52, v0 offset:18720
	v_cvt_pk_bf16_f32 v0, v78, v1
	ds_write_b16 v53, v0 offset:19296
	v_cvt_pk_bf16_f32 v0, v83, v1
	ds_write_b16 v52, v0 offset:18864
	v_cvt_pk_bf16_f32 v0, v79, v1
	ds_write_b16 v53, v0 offset:19440
	s_waitcnt vmcnt(0)
	v_cvt_pk_bf16_f32 v0, v88, v1
	ds_write_b16 v52, v0 offset:27648
	v_cvt_pk_bf16_f32 v0, v84, v1
	ds_write_b16 v53, v0 offset:28224
	v_cvt_pk_bf16_f32 v0, v89, v1
	ds_write_b16 v52, v0 offset:27792
	v_cvt_pk_bf16_f32 v0, v85, v1
	ds_write_b16 v53, v0 offset:28368
	v_cvt_pk_bf16_f32 v0, v90, v1
	ds_write_b16 v52, v0 offset:27936
	v_cvt_pk_bf16_f32 v0, v86, v1
	ds_write_b16 v53, v0 offset:28512
	v_cvt_pk_bf16_f32 v0, v91, v1
	ds_write_b16 v52, v0 offset:28080
	v_cvt_pk_bf16_f32 v0, v87, v1
	ds_write_b16 v53, v0 offset:28656
	v_add_u32_e32 v0, s1, v3
	v_ashrrev_i32_e32 v0, 4, v0
	s_waitcnt lgkmcnt(0)
	s_barrier
	ds_read_b128 v[60:63], v59
	v_and_b32_e32 v0, -16, v0
	v_add_u32_e32 v64, s0, v0
	v_ashrrev_i32_e32 v65, 31, v64
	v_lshlrev_b64 v[64:65], 15, v[64:65]
	v_add_u32_e32 v0, s1, v56
	v_lshl_add_u64 v[64:65], v[36:37], 0, v[64:65]
	v_ashrrev_i32_e32 v0, 4, v0
	s_waitcnt lgkmcnt(0)
	global_store_dwordx4 v[64:65], v[60:63], off
	ds_read_b128 v[60:63], v59 offset:9216
	v_and_b32_e32 v0, -16, v0
	v_add_u32_e32 v64, s0, v0
	v_ashrrev_i32_e32 v65, 31, v64
	v_lshlrev_b64 v[64:65], 15, v[64:65]
	v_add_u32_e32 v0, s1, v57
	v_lshl_add_u64 v[64:65], v[38:39], 0, v[64:65]
	v_ashrrev_i32_e32 v0, 4, v0
	s_waitcnt lgkmcnt(0)
	global_store_dwordx4 v[64:65], v[60:63], off
	ds_read_b128 v[60:63], v59 offset:18432
	v_and_b32_e32 v0, -16, v0
	v_add_u32_e32 v64, s0, v0
	v_ashrrev_i32_e32 v65, 31, v64
	v_lshlrev_b64 v[64:65], 15, v[64:65]
	v_add_u32_e32 v0, s1, v58
	v_lshl_add_u64 v[64:65], v[40:41], 0, v[64:65]
	v_ashrrev_i32_e32 v0, 4, v0
	s_waitcnt lgkmcnt(0)
	global_store_dwordx4 v[64:65], v[60:63], off
	ds_read_b128 v[60:63], v59 offset:27648
	v_and_b32_e32 v0, -16, v0
	v_add_u32_e32 v64, s0, v0
	v_ashrrev_i32_e32 v65, 31, v64
	v_lshlrev_b64 v[64:65], 15, v[64:65]
	v_lshl_add_u64 v[64:65], v[42:43], 0, v[64:65]
	s_waitcnt lgkmcnt(0)
	global_store_dwordx4 v[64:65], v[60:63], off
	s_barrier

; __device__ __forceinline__ bf16_t f2bf(float f) { return (bf16_t)(cvt_pk_bf16(f, 0.f) & 0xffffu); }
; __device__ __forceinline__ void cvt_tile(unsigned char* shm, int tid, const float* src, bf16_t* dst, int K, int N, int mode, const float* kscale, int ldd, int t) {
;     ...
;     { const int k = tid >> 3, n8 = (tid & 7) * 8;
;       const float* s = src + (size_t)(kt * 64 + k) * N + nti * 256 + n8; const float ks = kscale ? kscale[kt * 64 + k] : 1.0f;
;       f32x4 v[8];
; #pragma unroll
;       for (int q = 0; q < 4; ++q) { v[2 * q] = *(const f32x4*)(s + q * 64); v[2 * q + 1] = *(const f32x4*)(s + q * 64 + 4); }
;       asm volatile("" ::: "memory");
; #pragma unroll
;       for (int q = 0; q < 4; ++q)
; #pragma unroll
;           for (int j = 0; j < 4; ++j) { T[(q * 64 + n8 + j) * 72 + k] = f2bf(v[2 * q][j] * ks); T[(q * 64 + n8 + 4 + j) * 72 + k] = f2bf(v[2 * q + 1][j] * ks); } }
;     __syncthreads();
; #pragma unroll
;     for (int q = 0; q < 4; ++q) { const int n = q * 64 + (tid >> 3), k8 = (tid & 7) * 8; const int nn = nti * 256 + n;
;       const int drow = mode == 0 ? nn : ((nn >> 7) * 256 + (nn & 127) + (mode == 2 ? 128 : 0));
;       *(u32x4*)(dst + ((size_t)((drow >> 8) * (K / 64) + kt) * 256 + (drow & 255)) * 64 + k8) = *(const u32x4*)(T + n * 72 + k8); }
;     __syncthreads();
; __device__ __forceinline__ void cvt_mixer_tile(const Params& p, unsigned char* shm, int tid, bf16_t* W, int l, int t) {
;     if (t < 1728) cvt_tile(shm, tid, p.in[3] + (size_t)l * DM * 13824, W + W_IN, DM, 13824, 0, p.in[2] + (l * 6 + 2) * DM, LDX, t);
.LBB0_992:
	s_andn2_b64 vcc, exec, s[0:1]
	s_cbranch_vccnz .LBB0_967
	s_mul_hi_i32 s0, s2, 0x4bda12f7
	s_lshr_b32 s1, s0, 31
	s_ashr_i32 s0, s0, 4
	s_add_i32 s0, s0, s1
	v_lshl_add_u32 v60, s0, 6, v3
	v_ashrrev_i32_e32 v61, 31, v60
	v_lshl_add_u64 v[62:63], v[60:61], 2, s[64:65]
	global_load_dword v59, v[62:63], off
	v_mov_b64_e32 v[62:63], s[54:55]
	s_mov_b32 s1, 0xd800
	v_mad_i64_i32 v[60:61], s[4:5], v60, s1, v[62:63]
	s_mul_i32 s1, s0, 54
	s_sub_i32 s1, s2, s1
	s_lshl_b32 s40, s1, 8
	s_ashr_i32 s41, s40, 31
	v_lshl_add_u64 v[60:61], s[40:41], 2, v[60:61]
	v_lshlrev_b32_e32 v0, 2, v2
	v_lshl_add_u64 v[88:89], v[60:61], 0, v[0:1]
	global_load_dwordx4 v[60:63], v[88:89], off nt
	global_load_dwordx4 v[64:67], v[88:89], off offset:16 nt
	global_load_dwordx4 v[68:71], v[88:89], off offset:256 nt
	global_load_dwordx4 v[72:75], v[88:89], off offset:272 nt
	global_load_dwordx4 v[76:79], v[88:89], off offset:512 nt
	global_load_dwordx4 v[80:83], v[88:89], off offset:528 nt
	global_load_dwordx4 v[84:87], v[88:89], off offset:768 nt
	s_nop 0
	global_load_dwordx4 v[88:91], v[88:89], off offset:784 nt
	s_waitcnt vmcnt(7)
	v_mul_f32_e32 v0, v59, v60
	s_waitcnt vmcnt(6)
	v_mul_f32_e32 v60, v59, v64
	v_mul_f32_e32 v61, v59, v61
	v_mul_f32_e32 v64, v59, v65
	v_mul_f32_e32 v62, v59, v62
	v_mul_f32_e32 v65, v59, v66
	v_mul_f32_e32 v63, v59, v63
	v_mul_f32_e32 v66, v59, v67
	s_waitcnt vmcnt(5)
	v_mul_f32_e32 v67, v59, v68
	s_waitcnt vmcnt(4)
	v_mul_f32_e32 v68, v59, v72
	v_mul_f32_e32 v69, v59, v69
	v_mul_f32_e32 v72, v59, v73
	v_mul_f32_e32 v70, v59, v70
	v_mul_f32_e32 v73, v59, v74
	v_mul_f32_e32 v71, v59, v71
	v_mul_f32_e32 v74, v59, v75
	s_waitcnt vmcnt(3)
	v_mul_f32_e32 v75, v59, v76
	s_waitcnt vmcnt(2)
	v_mul_f32_e32 v76, v59, v80
	v_mul_f32_e32 v77, v59, v77
	v_mul_f32_e32 v80, v59, v81
	v_mul_f32_e32 v78, v59, v78
	v_mul_f32_e32 v81, v59, v82
	v_cvt_pk_bf16_f32 v0, v0, v1
	v_cvt_pk_bf16_f32 v60, v60, v1
	v_cvt_pk_bf16_f32 v61, v61, v1
	v_cvt_pk_bf16_f32 v64, v64, v1
	v_cvt_pk_bf16_f32 v62, v62, v1
	v_cvt_pk_bf16_f32 v65, v65, v1
	v_cvt_pk_bf16_f32 v63, v63, v1
	v_cvt_pk_bf16_f32 v66, v66, v1
	v_cvt_pk_bf16_f32 v67, v67, v1
	v_cvt_pk_bf16_f32 v68, v68, v1
	v_cvt_pk_bf16_f32 v69, v69, v1
	v_cvt_pk_bf16_f32 v72, v72, v1
	v_cvt_pk_bf16_f32 v70, v70, v1
	v_cvt_pk_bf16_f32 v73, v73, v1
	v_cvt_pk_bf16_f32 v71, v71, v1
	v_cvt_pk_bf16_f32 v74, v74, v1
	v_cvt_pk_bf16_f32 v75, v75, v1
	v_cvt_pk_bf16_f32 v76, v76, v1
	v_cvt_pk_bf16_f32 v77, v77, v1
	v_cvt_pk_bf16_f32 v80, v80, v1
	v_cvt_pk_bf16_f32 v78, v78, v1
	v_cvt_pk_bf16_f32 v81, v81, v1
	ds_write_b16 v52, v0
	ds_write_b16 v53, v60 offset:576
	ds_write_b16 v52, v61 offset:144
	ds_write_b16 v53, v64 offset:720
	ds_write_b16 v52, v62 offset:288
	ds_write_b16 v53, v65 offset:864
	ds_write_b16 v52, v63 offset:432
	ds_write_b16 v53, v66 offset:1008
	ds_write_b16 v52, v67 offset:9216
	ds_write_b16 v53, v68 offset:9792
	ds_write_b16 v52, v69 offset:9360
	ds_write_b16 v53, v72 offset:9936
	ds_write_b16 v52, v70 offset:9504
	ds_write_b16 v53, v73 offset:10080
	ds_write_b16 v52, v71 offset:9648
	ds_write_b16 v53, v74 offset:10224
	ds_write_b16 v52, v75 offset:18432
	ds_write_b16 v53, v76 offset:19008
	ds_write_b16 v52, v77 offset:18576
	ds_write_b16 v53, v80 offset:19152
	ds_write_b16 v52, v78 offset:18720
	ds_write_b16 v53, v81 offset:19296
	v_mul_f32_e32 v0, v59, v79
	v_cvt_pk_bf16_f32 v0, v0, v1
	ds_write_b16 v52, v0 offset:18864
	v_mul_f32_e32 v0, v59, v83
	v_cvt_pk_bf16_f32 v0, v0, v1
	ds_write_b16 v53, v0 offset:19440
	s_waitcnt vmcnt(1)
	v_mul_f32_e32 v0, v59, v84
	v_cvt_pk_bf16_f32 v0, v0, v1
	ds_write_b16 v52, v0 offset:27648
	s_waitcnt vmcnt(0)
	v_mul_f32_e32 v0, v59, v88
	v_cvt_pk_bf16_f32 v0, v0, v1
	ds_write_b16 v53, v0 offset:28224
	v_mul_f32_e32 v0, v59, v85
	v_cvt_pk_bf16_f32 v0, v0, v1
	ds_write_b16 v52, v0 offset:27792
	v_mul_f32_e32 v0, v59, v89
	v_cvt_pk_bf16_f32 v0, v0, v1
	ds_write_b16 v53, v0 offset:28368
	v_mul_f32_e32 v0, v59, v86
	v_cvt_pk_bf16_f32 v0, v0, v1
	ds_write_b16 v52, v0 offset:27936
	v_mul_f32_e32 v0, v59, v90
	v_cvt_pk_bf16_f32 v0, v0, v1
	ds_write_b16 v53, v0 offset:28512
	v_mul_f32_e32 v0, v59, v87
	v_cvt_pk_bf16_f32 v0, v0, v1
	ds_write_b16 v52, v0 offset:28080
	v_mul_f32_e32 v0, v59, v91
	v_cvt_pk_bf16_f32 v0, v0, v1
	ds_write_b16 v53, v0 offset:28656
	v_add_u32_e32 v0, s40, v3
	v_add_u32_e32 v59, v54, v55
	v_ashrrev_i32_e32 v0, 3, v0
	s_waitcnt lgkmcnt(0)
	s_barrier
	ds_read_b128 v[60:63], v59
	v_and_b32_e32 v0, 0xffffffe0, v0
	v_add_u32_e32 v64, s0, v0
	v_ashrrev_i32_e32 v65, 31, v64
	v_add_u32_e32 v0, s40, v56
	v_lshlrev_b64 v[64:65], 15, v[64:65]
	v_ashrrev_i32_e32 v0, 3, v0
	v_lshl_add_u64 v[68:69], v[44:45], 0, v[64:65]
	ds_read_b128 v[64:67], v59 offset:9216
	v_and_b32_e32 v0, 0xffffffe0, v0
	s_waitcnt lgkmcnt(1)
	global_store_dwordx4 v[68:69], v[60:63], off
	s_nop 1
	v_add_u32_e32 v60, s0, v0
	v_ashrrev_i32_e32 v61, 31, v60
	v_lshlrev_b64 v[60:61], 15, v[60:61]
	v_add_u32_e32 v0, s40, v57
	v_lshl_add_u64 v[60:61], v[46:47], 0, v[60:61]
	v_ashrrev_i32_e32 v0, 3, v0
	s_waitcnt lgkmcnt(0)
	global_store_dwordx4 v[60:61], v[64:67], off
	ds_read_b128 v[60:63], v59 offset:18432
	v_and_b32_e32 v0, 0xffffffe0, v0
	v_add_u32_e32 v64, s0, v0
	v_ashrrev_i32_e32 v65, 31, v64
	v_add_u32_e32 v0, s40, v58
	v_lshlrev_b64 v[64:65], 15, v[64:65]
	v_ashrrev_i32_e32 v0, 3, v0
	v_lshl_add_u64 v[68:69], v[48:49], 0, v[64:65]
	ds_read_b128 v[64:67], v59 offset:27648
	v_and_b32_e32 v0, 0xffffffe0, v0
	s_waitcnt lgkmcnt(1)
	global_store_dwordx4 v[68:69], v[60:63], off
	s_nop 1
	v_add_u32_e32 v60, s0, v0
	v_ashrrev_i32_e32 v61, 31, v60
	v_lshlrev_b64 v[60:61], 15, v[60:61]
	v_lshl_add_u64 v[60:61], v[50:51], 0, v[60:61]
	s_waitcnt lgkmcnt(0)
	global_store_dwordx4 v[60:61], v[64:67], off
	s_barrier
	s_branch .LBB0_967
